# combo2 + residual epilogues (out1/down0/down1): loads of row groups 1..6 hoisted to epilogue start with counted vmcnt
# baseline (speedup 1.0000x reference)
; __device__ __forceinline__ unsigned pk2(float lo, float hi) { f32x2_t v = {lo, hi}; bf16x2_t b = __builtin_convertvector(v, bf16x2_t); return __builtin_bit_cast(unsigned, b); }
; __device__ __forceinline__ float xor16_sum(float v) { const auto r = __builtin_amdgcn_permlane16_swap(__float_as_uint(v), __float_as_uint(v), false, false); return __uint_as_float(r[0]) + __uint_as_float(r[1]); }
; __device__ __forceinline__ float xor32_sum(float v) { const auto r = __builtin_amdgcn_permlane32_swap(__float_as_uint(v), __float_as_uint(v), false, false); return __uint_as_float(r[0]) + __uint_as_float(r[1]); }
; #define BF16_LO(w) __uint_as_float((w) << 16)
; #define BF16_HI(w) __uint_as_float((w) & 0xffff0000u)
;     __device__ __forceinline__ void operator()(const f32x4 (&acc)[2][2][4][2], const Unit& u, int wr, int wc, int fr_in, int fq_in) const {
;     ...
; #pragma unroll
;         for (int ai = 0; ai < 2; ++ai)
; #pragma unroll
;             for (int m = 0; m < 4; ++m) {
;                 const int row = u.pm * BM + ai * 128 + wr * 64 + m * 16 + fr;
;                 float s = 0.f;
; #pragma unroll
;                 for (int bj = 0; bj < 2; ++bj) {
;                     const size_t off = (size_t)row * DM + u.pn * BM + bj * HALF + wc * 32 + 8 * fq;
;                     f32x4 b0, b1;
;                     if (xbase) { b0 = *(const f32x4*)(xbase + off); b1 = *(const f32x4*)(xbase + off + 4); }
;                     else { const u32x4 q = *(const u32x4*)(hb + off);
;                         b0 = (f32x4){BF16_LO(q.x), BF16_HI(q.x), BF16_LO(q.y), BF16_HI(q.y)}; b1 = (f32x4){BF16_LO(q.z), BF16_HI(q.z), BF16_LO(q.w), BF16_HI(q.w)}; }
;                     const f32x4 h0 = b0 + acc[ai][bj][m][0], h1 = b1 + acc[ai][bj][m][1];
;                     u32x4 w; w.x = pk2(h0[0], h0[1]); w.y = pk2(h0[2], h0[3]); w.z = pk2(h1[0], h1[1]); w.w = pk2(h1[2], h1[3]);
;                     *(u32x4*)(hb + off) = w;
;                     s += (h0[0] * h0[0] + h0[1] * h0[1]) + (h0[2] * h0[2] + h0[3] * h0[3]) + (h1[0] * h1[0] + h1[1] * h1[1]) + (h1[2] * h1[2] + h1[3] * h1[3]);
;                 }
;                 s = xor32_sum(xor16_sum(s));
;                 if (fq == 0) xch[(ai * 128 + wr * 64 + m * 16 + fr) * 4 + wc] = s;
.LBB0_874:
	v_mov_b32_e32 v168, v149
	v_mov_b32_e32 v169, v148
	s_lshl_b32 s4, s54, 8
	v_add_u32_e32 v188, s39, v168
	v_add_u32_e32 v144, s4, v188
	s_lshl_b32 s0, s53, 8
	s_ashr_i32 s1, s0, 31
	v_lshlrev_b32_e32 v146, 3, v169
	v_ashrrev_i32_e32 v145, 31, v144
	v_ashrrev_i32_e32 v147, 31, v146
	s_or_b64 s[0:1], s[0:1], s[14:15]
	v_lshlrev_b64 v[170:171], 11, v[144:145]
	v_lshl_add_u64 v[146:147], s[0:1], 0, v[146:147]
	v_lshl_add_u64 v[170:171], s[8:9], 0, v[170:171]
	v_lshl_add_u64 v[178:179], v[146:147], 1, v[170:171]
	global_load_dwordx4 v[170:173], v[178:179], off
	global_load_dwordx4 v[174:177], v[178:179], off offset:256
	v_add_u32_e32 v190, 16, v144
	v_ashrrev_i32_e32 v191, 31, v190
	v_lshlrev_b64 v[190:191], 11, v[190:191]
	v_lshl_add_u64 v[190:191], s[8:9], 0, v[190:191]
	v_lshl_add_u64 v[190:191], v[146:147], 1, v[190:191]
	global_load_dwordx4 v[192:195], v[190:191], off
	global_load_dwordx4 v[196:199], v[190:191], off offset:256
	v_add_u32_e32 v200, 32, v144
	v_ashrrev_i32_e32 v201, 31, v200
	v_lshlrev_b64 v[200:201], 11, v[200:201]
	v_lshl_add_u64 v[200:201], s[8:9], 0, v[200:201]
	v_lshl_add_u64 v[200:201], v[146:147], 1, v[200:201]
	global_load_dwordx4 v[202:205], v[200:201], off
	global_load_dwordx4 v[206:209], v[200:201], off offset:256
	v_add_u32_e32 v210, 48, v144
	v_ashrrev_i32_e32 v211, 31, v210
	v_lshlrev_b64 v[210:211], 11, v[210:211]
	v_lshl_add_u64 v[210:211], s[8:9], 0, v[210:211]
	v_lshl_add_u64 v[210:211], v[146:147], 1, v[210:211]
	global_load_dwordx4 v[212:215], v[210:211], off
	global_load_dwordx4 v[216:219], v[210:211], off offset:256
	v_add_u32_e32 v220, 0x80, v144
	v_ashrrev_i32_e32 v221, 31, v220
	v_lshlrev_b64 v[220:221], 11, v[220:221]
	v_lshl_add_u64 v[220:221], s[8:9], 0, v[220:221]
	v_lshl_add_u64 v[220:221], v[146:147], 1, v[220:221]
	global_load_dwordx4 v[222:225], v[220:221], off
	global_load_dwordx4 v[226:229], v[220:221], off offset:256
	v_add_u32_e32 v230, 0x90, v144
	v_ashrrev_i32_e32 v231, 31, v230
	v_lshlrev_b64 v[230:231], 11, v[230:231]
	v_lshl_add_u64 v[230:231], s[8:9], 0, v[230:231]
	v_lshl_add_u64 v[230:231], v[146:147], 1, v[230:231]
	global_load_dwordx4 v[232:235], v[230:231], off
	global_load_dwordx4 v[236:239], v[230:231], off offset:256
	v_add_u32_e32 v240, 0xa0, v144
	v_ashrrev_i32_e32 v241, 31, v240
	v_lshlrev_b64 v[240:241], 11, v[240:241]
	v_lshl_add_u64 v[240:241], s[8:9], 0, v[240:241]
	v_lshl_add_u64 v[240:241], v[146:147], 1, v[240:241]
	global_load_dwordx4 v[242:245], v[240:241], off
	global_load_dwordx4 v[246:249], v[240:241], off offset:256
	v_cmp_eq_u32_e32 vcc, 0, v169
	s_waitcnt vmcnt(12)
	v_lshlrev_b32_e32 v180, 16, v170
	v_and_b32_e32 v181, 0xffff0000, v170
	v_lshlrev_b32_e32 v170, 16, v171
	v_and_b32_e32 v171, 0xffff0000, v171
	v_lshlrev_b32_e32 v182, 16, v172
	v_and_b32_e32 v183, 0xffff0000, v172
	v_lshlrev_b32_e32 v172, 16, v173
	v_and_b32_e32 v173, 0xffff0000, v173
	v_lshlrev_b32_e32 v184, 16, v174
	v_and_b32_e32 v185, 0xffff0000, v174
	v_lshlrev_b32_e32 v174, 16, v175
	v_and_b32_e32 v175, 0xffff0000, v175
	v_lshlrev_b32_e32 v186, 16, v176
	v_and_b32_e32 v187, 0xffff0000, v176
	v_lshlrev_b32_e32 v176, 16, v177
	v_and_b32_e32 v177, 0xffff0000, v177
	v_pk_add_f32 v[126:127], v[126:127], v[170:171]
	v_pk_add_f32 v[124:125], v[124:125], v[180:181]
	v_pk_add_f32 v[122:123], v[122:123], v[172:173]
	v_pk_add_f32 v[170:171], v[118:119], v[174:175]
	v_pk_add_f32 v[172:173], v[116:117], v[184:185]
	v_pk_add_f32 v[120:121], v[120:121], v[182:183]
	v_pk_add_f32 v[174:175], v[114:115], v[176:177]
	v_pk_add_f32 v[176:177], v[112:113], v[186:187]
	v_cvt_pk_bf16_f32 v112, v124, v125
	v_cvt_pk_bf16_f32 v113, v126, v127
	v_mul_f32_e32 v125, v125, v125
	v_mul_f32_e32 v127, v127, v127
	v_mul_f32_e32 v145, v173, v173
	v_mul_f32_e32 v169, v171, v171
	v_cvt_pk_bf16_f32 v114, v120, v121
	v_cvt_pk_bf16_f32 v115, v122, v123
	v_mul_f32_e32 v121, v121, v121
	v_cvt_pk_bf16_f32 v117, v170, v171
	v_mul_f32_e32 v171, v177, v177
	v_fmac_f32_e32 v125, v124, v124
	v_fmac_f32_e32 v127, v126, v126
	v_fmac_f32_e32 v145, v172, v172
	v_fmac_f32_e32 v169, v170, v170
	v_mul_f32_e32 v123, v123, v123
	v_cvt_pk_bf16_f32 v116, v172, v173
	v_mul_f32_e32 v173, v175, v175
	global_store_dwordx4 v[178:179], v[112:115], off
	v_fmac_f32_e32 v121, v120, v120
	v_fmac_f32_e32 v171, v176, v176
	v_add_f32_e32 v112, v125, v127
	v_add_f32_e32 v113, v145, v169
	v_fmac_f32_e32 v123, v122, v122
	v_fmac_f32_e32 v173, v174, v174
	v_add_f32_e32 v112, v121, v112
	v_add_f32_e32 v113, v171, v113
	v_add_f32_e32 v112, v123, v112
	v_add_f32_e32 v113, v173, v113
	v_add_f32_e32 v112, v112, v113
	v_mov_b32_e32 v113, v112
	s_nop 1
	v_permlane16_swap_b32_e32 v112, v113
	v_add_f32_e32 v113, v112, v113
	v_mov_b32_e32 v114, v113
	v_cvt_pk_bf16_f32 v118, v176, v177
	v_cvt_pk_bf16_f32 v119, v174, v175
	v_permlane32_swap_b32_e32 v113, v114
	v_lshl_add_u32 v112, v188, 4, s47
	global_store_dwordx4 v[178:179], v[116:119], off offset:256
	s_and_saveexec_b64 s[0:1], vcc
	v_add_f32_e32 v113, v113, v114
	ds_write_b32 v112, v113
	s_or_b64 exec, exec, s[0:1]
	s_waitcnt vmcnt(13)
	v_lshlrev_b32_e32 v124, 16, v192
	v_and_b32_e32 v125, 0xffff0000, v192
	v_lshlrev_b32_e32 v114, 16, v193
	v_and_b32_e32 v115, 0xffff0000, v193
	v_lshlrev_b32_e32 v126, 16, v194
	v_and_b32_e32 v127, 0xffff0000, v194
	v_lshlrev_b32_e32 v116, 16, v195
	v_and_b32_e32 v117, 0xffff0000, v195
	s_waitcnt vmcnt(12)
; __device__ __forceinline__ unsigned pk2(float lo, float hi) { f32x2_t v = {lo, hi}; bf16x2_t b = __builtin_convertvector(v, bf16x2_t); return __builtin_bit_cast(unsigned, b); }
; __device__ __forceinline__ float xor16_sum(float v) { const auto r = __builtin_amdgcn_permlane16_swap(__float_as_uint(v), __float_as_uint(v), false, false); return __uint_as_float(r[0]) + __uint_as_float(r[1]); }
; __device__ __forceinline__ float xor32_sum(float v) { const auto r = __builtin_amdgcn_permlane32_swap(__float_as_uint(v), __float_as_uint(v), false, false); return __uint_as_float(r[0]) + __uint_as_float(r[1]); }
; #define BF16_LO(w) __uint_as_float((w) << 16)
; #define BF16_HI(w) __uint_as_float((w) & 0xffff0000u)
;     __device__ __forceinline__ void operator()(const f32x4 (&acc)[2][2][4][2], const Unit& u, int wr, int wc, int fr_in, int fq_in) const {
;     ...
;             for (int m = 0; m < 4; ++m) {
;                 const int row = u.pm * BM + ai * 128 + wr * 64 + m * 16 + fr;
;                 float s = 0.f;
; #pragma unroll
;                 for (int bj = 0; bj < 2; ++bj) {
;                     const size_t off = (size_t)row * DM + u.pn * BM + bj * HALF + wc * 32 + 8 * fq;
;                     f32x4 b0, b1;
;                     if (xbase) { b0 = *(const f32x4*)(xbase + off); b1 = *(const f32x4*)(xbase + off + 4); }
;                     else { const u32x4 q = *(const u32x4*)(hb + off);
;                         b0 = (f32x4){BF16_LO(q.x), BF16_HI(q.x), BF16_LO(q.y), BF16_HI(q.y)}; b1 = (f32x4){BF16_LO(q.z), BF16_HI(q.z), BF16_LO(q.w), BF16_HI(q.w)}; }
;                     const f32x4 h0 = b0 + acc[ai][bj][m][0], h1 = b1 + acc[ai][bj][m][1];
;                     u32x4 w; w.x = pk2(h0[0], h0[1]); w.y = pk2(h0[2], h0[3]); w.z = pk2(h1[0], h1[1]); w.w = pk2(h1[2], h1[3]);
;                     *(u32x4*)(hb + off) = w;
;                     s += (h0[0] * h0[0] + h0[1] * h0[1]) + (h0[2] * h0[2] + h0[3] * h0[3]) + (h1[0] * h1[0] + h1[1] * h1[1]) + (h1[2] * h1[2] + h1[3] * h1[3]);
;                 }
;                 s = xor32_sum(xor16_sum(s));
;                 if (fq == 0) xch[(ai * 128 + wr * 64 + m * 16 + fr) * 4 + wc] = s;
	v_lshlrev_b32_e32 v170, 16, v196
	v_and_b32_e32 v171, 0xffff0000, v196
	v_lshlrev_b32_e32 v118, 16, v197
	v_and_b32_e32 v119, 0xffff0000, v197
	v_lshlrev_b32_e32 v172, 16, v198
	v_and_b32_e32 v173, 0xffff0000, v198
	v_lshlrev_b32_e32 v120, 16, v199
	v_and_b32_e32 v121, 0xffff0000, v199
	v_pk_add_f32 v[110:111], v[110:111], v[114:115]
	v_pk_add_f32 v[108:109], v[108:109], v[124:125]
	v_pk_add_f32 v[106:107], v[106:107], v[116:117]
	v_pk_add_f32 v[114:115], v[102:103], v[118:119]
	v_pk_add_f32 v[116:117], v[100:101], v[170:171]
	v_pk_add_f32 v[104:105], v[104:105], v[126:127]
	v_pk_add_f32 v[118:119], v[98:99], v[120:121]
	v_pk_add_f32 v[120:121], v[96:97], v[172:173]
	v_cvt_pk_bf16_f32 v96, v108, v109
	v_cvt_pk_bf16_f32 v97, v110, v111
	v_mul_f32_e32 v109, v109, v109
	v_mul_f32_e32 v111, v111, v111
	v_cvt_pk_bf16_f32 v101, v114, v115
	v_mul_f32_e32 v113, v117, v117
	v_mul_f32_e32 v115, v115, v115
	v_cvt_pk_bf16_f32 v98, v104, v105
	v_cvt_pk_bf16_f32 v99, v106, v107
	v_mul_f32_e32 v105, v105, v105
	v_cvt_pk_bf16_f32 v100, v116, v117
	v_mul_f32_e32 v117, v121, v121
	v_fmac_f32_e32 v109, v108, v108
	v_fmac_f32_e32 v111, v110, v110
	v_fmac_f32_e32 v113, v116, v116
	v_fmac_f32_e32 v115, v114, v114
	v_mul_f32_e32 v107, v107, v107
	v_cvt_pk_bf16_f32 v103, v118, v119
	v_mul_f32_e32 v119, v119, v119
	global_store_dwordx4 v[190:191], v[96:99], off
	v_fmac_f32_e32 v105, v104, v104
	v_fmac_f32_e32 v117, v120, v120
	v_add_f32_e32 v96, v109, v111
	v_add_f32_e32 v97, v113, v115
	v_fmac_f32_e32 v107, v106, v106
	v_fmac_f32_e32 v119, v118, v118
	v_add_f32_e32 v96, v105, v96
	v_add_f32_e32 v97, v117, v97
	v_add_f32_e32 v96, v107, v96
	v_add_f32_e32 v97, v119, v97
	v_add_f32_e32 v96, v96, v97
	v_mov_b32_e32 v97, v96
	s_nop 1
	v_permlane16_swap_b32_e32 v96, v97
	v_add_f32_e32 v96, v96, v97
	v_mov_b32_e32 v97, v96
	v_cvt_pk_bf16_f32 v102, v120, v121
	s_nop 0
	v_permlane32_swap_b32_e32 v96, v97
	global_store_dwordx4 v[190:191], v[100:103], off offset:256
	s_and_saveexec_b64 s[0:1], vcc
	v_add_f32_e32 v96, v96, v97
	ds_write_b32 v112, v96 offset:256
	s_or_b64 exec, exec, s[0:1]
	s_waitcnt vmcnt(13)
	v_lshlrev_b32_e32 v106, 16, v202
	v_and_b32_e32 v107, 0xffff0000, v202
	v_lshlrev_b32_e32 v96, 16, v203
	v_and_b32_e32 v97, 0xffff0000, v203
	v_lshlrev_b32_e32 v108, 16, v204
	v_and_b32_e32 v109, 0xffff0000, v204
	v_lshlrev_b32_e32 v98, 16, v205
	v_and_b32_e32 v99, 0xffff0000, v205
	s_waitcnt vmcnt(12)
	v_lshlrev_b32_e32 v110, 16, v206
	v_and_b32_e32 v111, 0xffff0000, v206
	v_lshlrev_b32_e32 v100, 16, v207
	v_and_b32_e32 v101, 0xffff0000, v207
	v_lshlrev_b32_e32 v114, 16, v208
	v_and_b32_e32 v115, 0xffff0000, v208
	v_lshlrev_b32_e32 v102, 16, v209
	v_and_b32_e32 v103, 0xffff0000, v209
	v_pk_add_f32 v[94:95], v[94:95], v[96:97]
	v_pk_add_f32 v[92:93], v[92:93], v[106:107]
	v_pk_add_f32 v[90:91], v[90:91], v[98:99]
	v_pk_add_f32 v[96:97], v[86:87], v[100:101]
	v_pk_add_f32 v[98:99], v[84:85], v[110:111]
	v_pk_add_f32 v[88:89], v[88:89], v[108:109]
	v_pk_add_f32 v[100:101], v[82:83], v[102:103]
	v_pk_add_f32 v[102:103], v[80:81], v[114:115]
	v_cvt_pk_bf16_f32 v80, v92, v93
	v_cvt_pk_bf16_f32 v81, v94, v95
	v_mul_f32_e32 v93, v93, v93
	v_mul_f32_e32 v95, v95, v95
	v_cvt_pk_bf16_f32 v84, v98, v99
	v_cvt_pk_bf16_f32 v85, v96, v97
	v_mul_f32_e32 v99, v99, v99
	v_mul_f32_e32 v97, v97, v97
	v_cvt_pk_bf16_f32 v82, v88, v89
	v_cvt_pk_bf16_f32 v83, v90, v91
	v_mul_f32_e32 v89, v89, v89
	v_cvt_pk_bf16_f32 v86, v102, v103
	v_mul_f32_e32 v103, v103, v103
	v_fmac_f32_e32 v93, v92, v92
	v_fmac_f32_e32 v95, v94, v94
	v_fmac_f32_e32 v99, v98, v98
	v_fmac_f32_e32 v97, v96, v96
	v_mul_f32_e32 v91, v91, v91
	v_cvt_pk_bf16_f32 v87, v100, v101
	v_mul_f32_e32 v101, v101, v101
	global_store_dwordx4 v[200:201], v[80:83], off
	v_fmac_f32_e32 v89, v88, v88
	v_fmac_f32_e32 v103, v102, v102
	v_add_f32_e32 v80, v93, v95
	v_add_f32_e32 v81, v99, v97
	v_fmac_f32_e32 v91, v90, v90
	v_fmac_f32_e32 v101, v100, v100
	v_add_f32_e32 v80, v89, v80
	v_add_f32_e32 v81, v103, v81
	v_add_f32_e32 v80, v91, v80
	v_add_f32_e32 v81, v101, v81
	v_add_f32_e32 v80, v80, v81
	v_mov_b32_e32 v81, v80
	s_nop 1
	v_permlane16_swap_b32_e32 v80, v81
	v_add_f32_e32 v80, v80, v81
	v_mov_b32_e32 v81, v80
	s_nop 1
	v_permlane32_swap_b32_e32 v80, v81
	global_store_dwordx4 v[200:201], v[84:87], off offset:256
	s_and_saveexec_b64 s[0:1], vcc
	v_add_f32_e32 v80, v80, v81
	ds_write_b32 v112, v80 offset:512
	s_or_b64 exec, exec, s[0:1]
	s_waitcnt vmcnt(13)
	v_lshlrev_b32_e32 v90, 16, v212
	v_and_b32_e32 v91, 0xffff0000, v212
	v_lshlrev_b32_e32 v80, 16, v213
	v_and_b32_e32 v81, 0xffff0000, v213
	v_lshlrev_b32_e32 v92, 16, v214
	v_and_b32_e32 v93, 0xffff0000, v214
	v_lshlrev_b32_e32 v82, 16, v215
	v_and_b32_e32 v83, 0xffff0000, v215
	s_waitcnt vmcnt(12)
; __device__ __forceinline__ unsigned pk2(float lo, float hi) { f32x2_t v = {lo, hi}; bf16x2_t b = __builtin_convertvector(v, bf16x2_t); return __builtin_bit_cast(unsigned, b); }
; __device__ __forceinline__ float xor16_sum(float v) { const auto r = __builtin_amdgcn_permlane16_swap(__float_as_uint(v), __float_as_uint(v), false, false); return __uint_as_float(r[0]) + __uint_as_float(r[1]); }
; __device__ __forceinline__ float xor32_sum(float v) { const auto r = __builtin_amdgcn_permlane32_swap(__float_as_uint(v), __float_as_uint(v), false, false); return __uint_as_float(r[0]) + __uint_as_float(r[1]); }
; #define BF16_LO(w) __uint_as_float((w) << 16)
; #define BF16_HI(w) __uint_as_float((w) & 0xffff0000u)
;     __device__ __forceinline__ void operator()(const f32x4 (&acc)[2][2][4][2], const Unit& u, int wr, int wc, int fr_in, int fq_in) const {
;     ...
; #pragma unroll
;         for (int ai = 0; ai < 2; ++ai)
; #pragma unroll
;             for (int m = 0; m < 4; ++m) {
;                 const int row = u.pm * BM + ai * 128 + wr * 64 + m * 16 + fr;
;                 float s = 0.f;
; #pragma unroll
;                 for (int bj = 0; bj < 2; ++bj) {
;                     const size_t off = (size_t)row * DM + u.pn * BM + bj * HALF + wc * 32 + 8 * fq;
;                     f32x4 b0, b1;
;                     if (xbase) { b0 = *(const f32x4*)(xbase + off); b1 = *(const f32x4*)(xbase + off + 4); }
;                     else { const u32x4 q = *(const u32x4*)(hb + off);
;                         b0 = (f32x4){BF16_LO(q.x), BF16_HI(q.x), BF16_LO(q.y), BF16_HI(q.y)}; b1 = (f32x4){BF16_LO(q.z), BF16_HI(q.z), BF16_LO(q.w), BF16_HI(q.w)}; }
;                     const f32x4 h0 = b0 + acc[ai][bj][m][0], h1 = b1 + acc[ai][bj][m][1];
;                     u32x4 w; w.x = pk2(h0[0], h0[1]); w.y = pk2(h0[2], h0[3]); w.z = pk2(h1[0], h1[1]); w.w = pk2(h1[2], h1[3]);
;                     *(u32x4*)(hb + off) = w;
;                     s += (h0[0] * h0[0] + h0[1] * h0[1]) + (h0[2] * h0[2] + h0[3] * h0[3]) + (h1[0] * h1[0] + h1[1] * h1[1]) + (h1[2] * h1[2] + h1[3] * h1[3]);
;                 }
;                 s = xor32_sum(xor16_sum(s));
;                 if (fq == 0) xch[(ai * 128 + wr * 64 + m * 16 + fr) * 4 + wc] = s;
;                 if (m == 3) asm volatile("" ::: "memory");
	v_lshlrev_b32_e32 v94, 16, v216
	v_and_b32_e32 v95, 0xffff0000, v216
	v_lshlrev_b32_e32 v84, 16, v217
	v_and_b32_e32 v85, 0xffff0000, v217
	v_lshlrev_b32_e32 v96, 16, v218
	v_and_b32_e32 v97, 0xffff0000, v218
	v_lshlrev_b32_e32 v86, 16, v219
	v_and_b32_e32 v87, 0xffff0000, v219
	v_pk_add_f32 v[78:79], v[78:79], v[80:81]
	v_pk_add_f32 v[76:77], v[76:77], v[90:91]
	v_pk_add_f32 v[74:75], v[74:75], v[82:83]
	v_pk_add_f32 v[80:81], v[70:71], v[84:85]
	v_pk_add_f32 v[82:83], v[68:69], v[94:95]
	v_pk_add_f32 v[72:73], v[72:73], v[92:93]
	v_pk_add_f32 v[84:85], v[66:67], v[86:87]
	v_pk_add_f32 v[86:87], v[64:65], v[96:97]
	v_cvt_pk_bf16_f32 v64, v76, v77
	v_cvt_pk_bf16_f32 v65, v78, v79
	v_mul_f32_e32 v77, v77, v77
	v_mul_f32_e32 v79, v79, v79
	v_cvt_pk_bf16_f32 v68, v82, v83
	v_cvt_pk_bf16_f32 v69, v80, v81
	v_mul_f32_e32 v83, v83, v83
	v_mul_f32_e32 v81, v81, v81
	v_cvt_pk_bf16_f32 v66, v72, v73
	v_cvt_pk_bf16_f32 v67, v74, v75
	v_mul_f32_e32 v73, v73, v73
	v_cvt_pk_bf16_f32 v70, v86, v87
	v_mul_f32_e32 v87, v87, v87
	v_fmac_f32_e32 v77, v76, v76
	v_fmac_f32_e32 v79, v78, v78
	v_fmac_f32_e32 v83, v82, v82
	v_fmac_f32_e32 v81, v80, v80
	v_mul_f32_e32 v75, v75, v75
	v_cvt_pk_bf16_f32 v71, v84, v85
	v_mul_f32_e32 v85, v85, v85
	global_store_dwordx4 v[210:211], v[64:67], off
	v_fmac_f32_e32 v73, v72, v72
	v_fmac_f32_e32 v87, v86, v86
	v_add_f32_e32 v64, v77, v79
	v_add_f32_e32 v65, v83, v81
	v_fmac_f32_e32 v75, v74, v74
	v_fmac_f32_e32 v85, v84, v84
	v_add_f32_e32 v64, v73, v64
	v_add_f32_e32 v65, v87, v65
	v_add_f32_e32 v64, v75, v64
	v_add_f32_e32 v65, v85, v65
	v_add_f32_e32 v64, v64, v65
	v_mov_b32_e32 v65, v64
	s_nop 1
	v_permlane16_swap_b32_e32 v64, v65
	v_add_f32_e32 v64, v64, v65
	v_mov_b32_e32 v65, v64
	s_nop 1
	v_permlane32_swap_b32_e32 v64, v65
	global_store_dwordx4 v[210:211], v[68:71], off offset:256
	s_and_saveexec_b64 s[0:1], vcc
	v_add_f32_e32 v64, v64, v65
	ds_write_b32 v112, v64 offset:768
	s_or_b64 exec, exec, s[0:1]
	s_waitcnt vmcnt(13)
	v_lshlrev_b32_e32 v74, 16, v222
	v_and_b32_e32 v75, 0xffff0000, v222
	v_lshlrev_b32_e32 v64, 16, v223
	v_and_b32_e32 v65, 0xffff0000, v223
	v_lshlrev_b32_e32 v76, 16, v224
	v_and_b32_e32 v77, 0xffff0000, v224
	v_lshlrev_b32_e32 v66, 16, v225
	v_and_b32_e32 v67, 0xffff0000, v225
	s_waitcnt vmcnt(12)
	v_lshlrev_b32_e32 v78, 16, v226
	v_and_b32_e32 v79, 0xffff0000, v226
	v_lshlrev_b32_e32 v68, 16, v227
	v_and_b32_e32 v69, 0xffff0000, v227
	v_lshlrev_b32_e32 v80, 16, v228
	v_and_b32_e32 v81, 0xffff0000, v228
	v_lshlrev_b32_e32 v70, 16, v229
	v_and_b32_e32 v71, 0xffff0000, v229
	v_pk_add_f32 v[62:63], v[62:63], v[64:65]
	v_pk_add_f32 v[60:61], v[60:61], v[74:75]
	v_pk_add_f32 v[58:59], v[58:59], v[66:67]
	v_pk_add_f32 v[64:65], v[54:55], v[68:69]
	v_pk_add_f32 v[66:67], v[52:53], v[78:79]
	v_pk_add_f32 v[56:57], v[56:57], v[76:77]
	v_pk_add_f32 v[68:69], v[50:51], v[70:71]
	v_pk_add_f32 v[70:71], v[48:49], v[80:81]
	v_cvt_pk_bf16_f32 v48, v60, v61
	v_cvt_pk_bf16_f32 v49, v62, v63
	v_mul_f32_e32 v61, v61, v61
	v_mul_f32_e32 v63, v63, v63
	v_cvt_pk_bf16_f32 v52, v66, v67
	v_cvt_pk_bf16_f32 v53, v64, v65
	v_mul_f32_e32 v67, v67, v67
	v_mul_f32_e32 v65, v65, v65
	v_cvt_pk_bf16_f32 v50, v56, v57
	v_cvt_pk_bf16_f32 v51, v58, v59
	v_mul_f32_e32 v57, v57, v57
	v_cvt_pk_bf16_f32 v54, v70, v71
	v_mul_f32_e32 v71, v71, v71
	v_fmac_f32_e32 v61, v60, v60
	v_fmac_f32_e32 v63, v62, v62
	v_fmac_f32_e32 v67, v66, v66
	v_fmac_f32_e32 v65, v64, v64
	v_mul_f32_e32 v59, v59, v59
	v_cvt_pk_bf16_f32 v55, v68, v69
	v_mul_f32_e32 v69, v69, v69
	global_store_dwordx4 v[220:221], v[48:51], off
	v_fmac_f32_e32 v57, v56, v56
	v_fmac_f32_e32 v71, v70, v70
	v_add_f32_e32 v48, v61, v63
	v_add_f32_e32 v49, v67, v65
	v_fmac_f32_e32 v59, v58, v58
	v_fmac_f32_e32 v69, v68, v68
	v_add_f32_e32 v48, v57, v48
	v_add_f32_e32 v49, v71, v49
	v_add_f32_e32 v48, v59, v48
	v_add_f32_e32 v49, v69, v49
	v_add_f32_e32 v48, v48, v49
	v_mov_b32_e32 v49, v48
	s_nop 1
	v_permlane16_swap_b32_e32 v48, v49
	v_add_f32_e32 v48, v48, v49
	v_mov_b32_e32 v49, v48
	s_nop 1
	v_permlane32_swap_b32_e32 v48, v49
	global_store_dwordx4 v[220:221], v[52:55], off offset:256
	s_and_saveexec_b64 s[0:1], vcc
	v_add_f32_e32 v48, v48, v49
	ds_write_b32 v112, v48 offset:2048
	s_or_b64 exec, exec, s[0:1]
	s_waitcnt vmcnt(13)
	v_lshlrev_b32_e32 v58, 16, v232
	v_and_b32_e32 v59, 0xffff0000, v232
	v_lshlrev_b32_e32 v48, 16, v233
	v_and_b32_e32 v49, 0xffff0000, v233
	v_lshlrev_b32_e32 v60, 16, v234
	v_and_b32_e32 v61, 0xffff0000, v234
	v_lshlrev_b32_e32 v50, 16, v235
	v_and_b32_e32 v51, 0xffff0000, v235
	s_waitcnt vmcnt(12)
	v_lshlrev_b32_e32 v62, 16, v236
	v_and_b32_e32 v63, 0xffff0000, v236
	v_lshlrev_b32_e32 v52, 16, v237
	v_and_b32_e32 v53, 0xffff0000, v237
	v_lshlrev_b32_e32 v64, 16, v238
	v_and_b32_e32 v65, 0xffff0000, v238
	v_lshlrev_b32_e32 v54, 16, v239
	v_and_b32_e32 v55, 0xffff0000, v239
	v_pk_add_f32 v[46:47], v[46:47], v[48:49]
	v_pk_add_f32 v[44:45], v[44:45], v[58:59]
	v_pk_add_f32 v[42:43], v[42:43], v[50:51]
	v_pk_add_f32 v[48:49], v[38:39], v[52:53]
	v_pk_add_f32 v[50:51], v[36:37], v[62:63]
	v_pk_add_f32 v[40:41], v[40:41], v[60:61]
	v_pk_add_f32 v[52:53], v[34:35], v[54:55]
	v_pk_add_f32 v[54:55], v[32:33], v[64:65]
	v_cvt_pk_bf16_f32 v32, v44, v45
	v_cvt_pk_bf16_f32 v33, v46, v47
	v_mul_f32_e32 v45, v45, v45
	v_mul_f32_e32 v47, v47, v47
	v_cvt_pk_bf16_f32 v36, v50, v51
	v_cvt_pk_bf16_f32 v37, v48, v49
	v_mul_f32_e32 v51, v51, v51
	v_mul_f32_e32 v49, v49, v49
	v_cvt_pk_bf16_f32 v34, v40, v41
	v_cvt_pk_bf16_f32 v35, v42, v43
	v_mul_f32_e32 v41, v41, v41
	v_cvt_pk_bf16_f32 v38, v54, v55
	v_mul_f32_e32 v55, v55, v55
	v_fmac_f32_e32 v45, v44, v44
	v_fmac_f32_e32 v47, v46, v46
	v_fmac_f32_e32 v51, v50, v50
	v_fmac_f32_e32 v49, v48, v48
	v_mul_f32_e32 v43, v43, v43
	v_cvt_pk_bf16_f32 v39, v52, v53
	v_mul_f32_e32 v53, v53, v53
	global_store_dwordx4 v[230:231], v[32:35], off
	v_fmac_f32_e32 v41, v40, v40
	v_fmac_f32_e32 v55, v54, v54
	v_add_f32_e32 v32, v45, v47
	v_add_f32_e32 v33, v51, v49
	v_fmac_f32_e32 v43, v42, v42
	v_fmac_f32_e32 v53, v52, v52
	v_add_f32_e32 v32, v41, v32
	v_add_f32_e32 v33, v55, v33
	v_add_f32_e32 v32, v43, v32
	v_add_f32_e32 v33, v53, v33
	v_add_f32_e32 v32, v32, v33
	v_mov_b32_e32 v33, v32
	s_nop 1
	v_permlane16_swap_b32_e32 v32, v33
	v_add_f32_e32 v32, v32, v33
	v_mov_b32_e32 v33, v32
	s_nop 1
	v_permlane32_swap_b32_e32 v32, v33
	global_store_dwordx4 v[230:231], v[36:39], off offset:256
	s_and_saveexec_b64 s[0:1], vcc
	v_add_f32_e32 v32, v32, v33
	ds_write_b32 v112, v32 offset:2304
	s_or_b64 exec, exec, s[0:1]
	s_waitcnt vmcnt(13)
; __device__ __forceinline__ unsigned pk2(float lo, float hi) { f32x2_t v = {lo, hi}; bf16x2_t b = __builtin_convertvector(v, bf16x2_t); return __builtin_bit_cast(unsigned, b); }
; __device__ __forceinline__ float xor16_sum(float v) { const auto r = __builtin_amdgcn_permlane16_swap(__float_as_uint(v), __float_as_uint(v), false, false); return __uint_as_float(r[0]) + __uint_as_float(r[1]); }
;     __device__ __forceinline__ void operator()(const f32x4 (&acc)[2][2][4][2], const Unit& u, int wr, int wc, int fr_in, int fq_in) const {
;     ...
; #pragma unroll
;         for (int ai = 0; ai < 2; ++ai)
; #pragma unroll
;             for (int m = 0; m < 4; ++m) {
;                 const int row = u.pm * BM + ai * 128 + wr * 64 + m * 16 + fr;
;                 float s = 0.f;
; #pragma unroll
;                 for (int bj = 0; bj < 2; ++bj) {
;                     const size_t off = (size_t)row * DM + u.pn * BM + bj * HALF + wc * 32 + 8 * fq;
;                     f32x4 b0, b1;
;                     if (xbase) { b0 = *(const f32x4*)(xbase + off); b1 = *(const f32x4*)(xbase + off + 4); }
;                     else { const u32x4 q = *(const u32x4*)(hb + off);
;                         b0 = (f32x4){BF16_LO(q.x), BF16_HI(q.x), BF16_LO(q.y), BF16_HI(q.y)}; b1 = (f32x4){BF16_LO(q.z), BF16_HI(q.z), BF16_LO(q.w), BF16_HI(q.w)}; }
;                     const f32x4 h0 = b0 + acc[ai][bj][m][0], h1 = b1 + acc[ai][bj][m][1];
;                     u32x4 w; w.x = pk2(h0[0], h0[1]); w.y = pk2(h0[2], h0[3]); w.z = pk2(h1[0], h1[1]); w.w = pk2(h1[2], h1[3]);
;                     *(u32x4*)(hb + off) = w;
;                     s += (h0[0] * h0[0] + h0[1] * h0[1]) + (h0[2] * h0[2] + h0[3] * h0[3]) + (h1[0] * h1[0] + h1[1] * h1[1]) + (h1[2] * h1[2] + h1[3] * h1[3]);
;                 }
;                 s = xor32_sum(xor16_sum(s));
;                 if (fq == 0) xch[(ai * 128 + wr * 64 + m * 16 + fr) * 4 + wc] = s;
;                 if (m == 3) asm volatile("" ::: "memory");
;             }
;         PG8_EPI_BAR();
;         if (fq == 0) {
; #pragma unroll
;             for (int ai = 0; ai < 2; ++ai) {
;                 const int rl = ai * 128 + wr * 64 + wc * 16 + fr;
;                 const f32x4 p = *(const PG8_LAS f32x4*)(xch + rl * 4);
;                 const float t = (p[0] + p[1]) + (p[2] + p[3]);
;                 atomicAdd(rsq + u.pm * BM + rl, (u64_t)(t * 16777216.0f));
;             }
	v_lshlrev_b32_e32 v42, 16, v242
	v_and_b32_e32 v43, 0xffff0000, v242
	v_lshlrev_b32_e32 v32, 16, v243
	v_and_b32_e32 v33, 0xffff0000, v243
	v_lshlrev_b32_e32 v44, 16, v244
	v_and_b32_e32 v45, 0xffff0000, v244
	v_lshlrev_b32_e32 v34, 16, v245
	v_and_b32_e32 v35, 0xffff0000, v245
	s_waitcnt vmcnt(12)
	v_lshlrev_b32_e32 v46, 16, v246
	v_and_b32_e32 v47, 0xffff0000, v246
	v_lshlrev_b32_e32 v36, 16, v247
	v_and_b32_e32 v37, 0xffff0000, v247
	v_lshlrev_b32_e32 v48, 16, v248
	v_and_b32_e32 v49, 0xffff0000, v248
	v_lshlrev_b32_e32 v38, 16, v249
	v_and_b32_e32 v39, 0xffff0000, v249
	v_pk_add_f32 v[30:31], v[30:31], v[32:33]
	v_pk_add_f32 v[28:29], v[28:29], v[42:43]
	v_pk_add_f32 v[26:27], v[26:27], v[34:35]
	v_pk_add_f32 v[32:33], v[22:23], v[36:37]
	v_pk_add_f32 v[34:35], v[20:21], v[46:47]
	v_pk_add_f32 v[24:25], v[24:25], v[44:45]
	v_pk_add_f32 v[36:37], v[18:19], v[38:39]
	v_pk_add_f32 v[38:39], v[16:17], v[48:49]
	v_cvt_pk_bf16_f32 v16, v28, v29
	v_cvt_pk_bf16_f32 v17, v30, v31
	v_mul_f32_e32 v29, v29, v29
	v_mul_f32_e32 v31, v31, v31
	v_cvt_pk_bf16_f32 v20, v34, v35
	v_cvt_pk_bf16_f32 v21, v32, v33
	v_mul_f32_e32 v35, v35, v35
	v_mul_f32_e32 v33, v33, v33
	v_cvt_pk_bf16_f32 v18, v24, v25
	v_cvt_pk_bf16_f32 v19, v26, v27
	v_mul_f32_e32 v25, v25, v25
	v_cvt_pk_bf16_f32 v22, v38, v39
	v_mul_f32_e32 v39, v39, v39
	v_fmac_f32_e32 v29, v28, v28
	v_fmac_f32_e32 v31, v30, v30
	v_fmac_f32_e32 v35, v34, v34
	v_fmac_f32_e32 v33, v32, v32
	v_mul_f32_e32 v27, v27, v27
	v_cvt_pk_bf16_f32 v23, v36, v37
	v_mul_f32_e32 v37, v37, v37
	global_store_dwordx4 v[240:241], v[16:19], off
	v_fmac_f32_e32 v25, v24, v24
	v_fmac_f32_e32 v39, v38, v38
	v_add_f32_e32 v16, v29, v31
	v_add_f32_e32 v17, v35, v33
	v_fmac_f32_e32 v27, v26, v26
	v_fmac_f32_e32 v37, v36, v36
	v_add_f32_e32 v16, v25, v16
	v_add_f32_e32 v17, v39, v17
	v_add_f32_e32 v16, v27, v16
	v_add_f32_e32 v17, v37, v17
	v_add_f32_e32 v16, v16, v17
	v_mov_b32_e32 v17, v16
	s_nop 1
	v_permlane16_swap_b32_e32 v16, v17
	v_add_f32_e32 v16, v16, v17
	v_mov_b32_e32 v17, v16
	s_nop 1
	v_permlane32_swap_b32_e32 v16, v17
	global_store_dwordx4 v[240:241], v[20:23], off offset:256
	s_and_saveexec_b64 s[0:1], vcc
	v_add_f32_e32 v16, v16, v17
	ds_write_b32 v112, v16 offset:2560
	s_or_b64 exec, exec, s[0:1]
	v_add_u32_e32 v16, 0xb0, v144
	v_ashrrev_i32_e32 v17, 31, v16
	v_lshlrev_b64 v[16:17], 11, v[16:17]
	v_lshl_add_u64 v[16:17], s[8:9], 0, v[16:17]
	v_lshl_add_u64 v[24:25], v[146:147], 1, v[16:17]
	global_load_dwordx4 v[16:19], v[24:25], off
	global_load_dwordx4 v[20:23], v[24:25], off offset:256
	s_waitcnt vmcnt(1)
	v_lshlrev_b32_e32 v26, 16, v16
	v_and_b32_e32 v27, 0xffff0000, v16
	v_lshlrev_b32_e32 v16, 16, v17
	v_and_b32_e32 v17, 0xffff0000, v17
	v_lshlrev_b32_e32 v28, 16, v18
	v_and_b32_e32 v29, 0xffff0000, v18
	v_lshlrev_b32_e32 v18, 16, v19
	v_and_b32_e32 v19, 0xffff0000, v19
	s_waitcnt vmcnt(0)
	v_lshlrev_b32_e32 v30, 16, v20
	v_and_b32_e32 v31, 0xffff0000, v20
	v_lshlrev_b32_e32 v20, 16, v21
	v_and_b32_e32 v21, 0xffff0000, v21
	v_lshlrev_b32_e32 v32, 16, v22
	v_and_b32_e32 v33, 0xffff0000, v22
	v_lshlrev_b32_e32 v22, 16, v23
	v_and_b32_e32 v23, 0xffff0000, v23
	v_pk_add_f32 v[14:15], v[14:15], v[16:17]
	v_pk_add_f32 v[12:13], v[12:13], v[26:27]
	v_pk_add_f32 v[10:11], v[10:11], v[18:19]
	v_pk_add_f32 v[16:17], v[6:7], v[20:21]
	v_pk_add_f32 v[18:19], v[4:5], v[30:31]
	v_pk_add_f32 v[8:9], v[8:9], v[28:29]
	v_pk_add_f32 v[20:21], v[2:3], v[22:23]
	v_pk_add_f32 v[22:23], v[0:1], v[32:33]
	v_cvt_pk_bf16_f32 v0, v12, v13
	v_cvt_pk_bf16_f32 v1, v14, v15
	v_mul_f32_e32 v13, v13, v13
	v_mul_f32_e32 v15, v15, v15
	v_cvt_pk_bf16_f32 v4, v18, v19
	v_cvt_pk_bf16_f32 v5, v16, v17
	v_mul_f32_e32 v19, v19, v19
	v_mul_f32_e32 v17, v17, v17
	v_cvt_pk_bf16_f32 v2, v8, v9
	v_cvt_pk_bf16_f32 v3, v10, v11
	v_mul_f32_e32 v9, v9, v9
	v_cvt_pk_bf16_f32 v6, v22, v23
	v_mul_f32_e32 v23, v23, v23
	v_fmac_f32_e32 v13, v12, v12
	v_fmac_f32_e32 v15, v14, v14
	v_fmac_f32_e32 v19, v18, v18
	v_fmac_f32_e32 v17, v16, v16
	v_mul_f32_e32 v11, v11, v11
	v_cvt_pk_bf16_f32 v7, v20, v21
	v_mul_f32_e32 v21, v21, v21
	global_store_dwordx4 v[24:25], v[0:3], off
	v_fmac_f32_e32 v9, v8, v8
	v_fmac_f32_e32 v23, v22, v22
	v_add_f32_e32 v0, v13, v15
	v_add_f32_e32 v1, v19, v17
	v_fmac_f32_e32 v11, v10, v10
	v_fmac_f32_e32 v21, v20, v20
	v_add_f32_e32 v0, v9, v0
	v_add_f32_e32 v1, v23, v1
	v_add_f32_e32 v0, v11, v0
	v_add_f32_e32 v1, v21, v1
	v_add_f32_e32 v0, v0, v1
	v_mov_b32_e32 v1, v0
	s_nop 1
	v_permlane16_swap_b32_e32 v0, v1
	v_add_f32_e32 v0, v0, v1
	v_mov_b32_e32 v1, v0
	s_nop 1
	v_permlane32_swap_b32_e32 v0, v1
	global_store_dwordx4 v[24:25], v[4:7], off offset:256
	s_and_saveexec_b64 s[0:1], vcc
	v_add_f32_e32 v0, v0, v1
	ds_write_b32 v112, v0 offset:2816
	s_or_b64 exec, exec, s[0:1]
	s_waitcnt lgkmcnt(0)
	s_barrier
	s_and_saveexec_b64 s[0:1], vcc
	s_cbranch_execz .LBB0_892
	v_add_u32_e32 v4, s46, v168
	v_lshl_add_u32 v6, v4, 4, v167
	ds_read_b128 v[0:3], v6
	s_ashr_i32 s5, s4, 31
	s_lshl_b64 s[4:5], s[4:5], 3
	s_add_u32 s4, s37, s4
	s_addc_u32 s5, s38, s5
	s_waitcnt lgkmcnt(0)
	v_add_f32_e32 v0, v0, v1
	v_add_f32_e32 v1, v2, v3
	v_add_f32_e32 v0, v0, v1
	v_mul_f32_e32 v0, 0x4b800000, v0
	v_trunc_f32_e32 v0, v0
	v_mul_f32_e32 v1, 0x2f800000, v0
	v_floor_f32_e32 v1, v1
	v_fmac_f32_e32 v0, 0xcf800000, v1
	v_cvt_u32_f32_e32 v0, v0
	v_cvt_u32_f32_e32 v1, v1
	v_ashrrev_i32_e32 v5, 31, v4
	v_lshl_add_u64 v[4:5], v[4:5], 3, s[4:5]
	global_atomic_add_x2 v[4:5], v[0:1], off
	ds_read_b128 v[0:3], v6 offset:2048
	s_waitcnt lgkmcnt(0)
	v_add_f32_e32 v0, v0, v1
	v_add_f32_e32 v1, v2, v3
	v_add_f32_e32 v0, v0, v1
	v_mul_f32_e32 v0, 0x4b800000, v0
	v_trunc_f32_e32 v0, v0
	v_mul_f32_e32 v1, 0x2f800000, v0
	v_floor_f32_e32 v1, v1
	v_fmac_f32_e32 v0, 0xcf800000, v1
	v_cvt_u32_f32_e32 v0, v0
	v_cvt_u32_f32_e32 v1, v1
	global_atomic_add_x2 v[4:5], v[0:1], off offset:1024

; __device__ __forceinline__ unsigned pk2(float lo, float hi) { f32x2_t v = {lo, hi}; bf16x2_t b = __builtin_convertvector(v, bf16x2_t); return __builtin_bit_cast(unsigned, b); }
; __device__ __forceinline__ float xor16_sum(float v) { const auto r = __builtin_amdgcn_permlane16_swap(__float_as_uint(v), __float_as_uint(v), false, false); return __uint_as_float(r[0]) + __uint_as_float(r[1]); }
; __device__ __forceinline__ float xor32_sum(float v) { const auto r = __builtin_amdgcn_permlane32_swap(__float_as_uint(v), __float_as_uint(v), false, false); return __uint_as_float(r[0]) + __uint_as_float(r[1]); }
; #define BF16_LO(w) __uint_as_float((w) << 16)
; #define BF16_HI(w) __uint_as_float((w) & 0xffff0000u)
;     __device__ __forceinline__ void operator()(const f32x4 (&acc)[2][2][4][2], const Unit& u, int wr, int wc, int fr_in, int fq_in) const {
;     ...
; #pragma unroll
;         for (int ai = 0; ai < 2; ++ai)
; #pragma unroll
;             for (int m = 0; m < 4; ++m) {
;                 const int row = u.pm * BM + ai * 128 + wr * 64 + m * 16 + fr;
;                 float s = 0.f;
; #pragma unroll
;                 for (int bj = 0; bj < 2; ++bj) {
;                     const size_t off = (size_t)row * DM + u.pn * BM + bj * HALF + wc * 32 + 8 * fq;
;                     f32x4 b0, b1;
;                     if (xbase) { b0 = *(const f32x4*)(xbase + off); b1 = *(const f32x4*)(xbase + off + 4); }
;                     else { const u32x4 q = *(const u32x4*)(hb + off);
;                         b0 = (f32x4){BF16_LO(q.x), BF16_HI(q.x), BF16_LO(q.y), BF16_HI(q.y)}; b1 = (f32x4){BF16_LO(q.z), BF16_HI(q.z), BF16_LO(q.w), BF16_HI(q.w)}; }
;                     const f32x4 h0 = b0 + acc[ai][bj][m][0], h1 = b1 + acc[ai][bj][m][1];
;                     u32x4 w; w.x = pk2(h0[0], h0[1]); w.y = pk2(h0[2], h0[3]); w.z = pk2(h1[0], h1[1]); w.w = pk2(h1[2], h1[3]);
;                     *(u32x4*)(hb + off) = w;
;                     s += (h0[0] * h0[0] + h0[1] * h0[1]) + (h0[2] * h0[2] + h0[3] * h0[3]) + (h1[0] * h1[0] + h1[1] * h1[1]) + (h1[2] * h1[2] + h1[3] * h1[3]);
;                 }
;                 s = xor32_sum(xor16_sum(s));
;                 if (fq == 0) xch[(ai * 128 + wr * 64 + m * 16 + fr) * 4 + wc] = s;
;                 if (m == 3) asm volatile("" ::: "memory");
.LBB0_1462:
	v_mov_b32_e32 v169, v148
	v_mov_b32_e32 v168, v149
	s_lshl_b32 s26, s26, 8
	v_add_u32_e32 v188, s44, v168
	v_add_u32_e32 v144, s26, v188
	s_lshl_b32 s0, s4, 8
	s_ashr_i32 s1, s0, 31
	v_lshlrev_b32_e32 v146, 3, v169
	v_ashrrev_i32_e32 v145, 31, v144
	v_ashrrev_i32_e32 v147, 31, v146
	s_or_b64 s[0:1], s[0:1], s[12:13]
	v_lshlrev_b64 v[170:171], 11, v[144:145]
	v_lshl_add_u64 v[146:147], s[0:1], 0, v[146:147]
	v_lshl_add_u64 v[170:171], s[10:11], 0, v[170:171]
	v_lshl_add_u64 v[178:179], v[146:147], 1, v[170:171]
	global_load_dwordx4 v[170:173], v[178:179], off
	global_load_dwordx4 v[174:177], v[178:179], off offset:256
	v_add_u32_e32 v190, 16, v144
	v_ashrrev_i32_e32 v191, 31, v190
	v_lshlrev_b64 v[190:191], 11, v[190:191]
	v_lshl_add_u64 v[190:191], s[10:11], 0, v[190:191]
	v_lshl_add_u64 v[190:191], v[146:147], 1, v[190:191]
	global_load_dwordx4 v[192:195], v[190:191], off
	global_load_dwordx4 v[196:199], v[190:191], off offset:256
	v_add_u32_e32 v200, 32, v144
	v_ashrrev_i32_e32 v201, 31, v200
	v_lshlrev_b64 v[200:201], 11, v[200:201]
	v_lshl_add_u64 v[200:201], s[10:11], 0, v[200:201]
	v_lshl_add_u64 v[200:201], v[146:147], 1, v[200:201]
	global_load_dwordx4 v[202:205], v[200:201], off
	global_load_dwordx4 v[206:209], v[200:201], off offset:256
	v_add_u32_e32 v210, 48, v144
	v_ashrrev_i32_e32 v211, 31, v210
	v_lshlrev_b64 v[210:211], 11, v[210:211]
	v_lshl_add_u64 v[210:211], s[10:11], 0, v[210:211]
	v_lshl_add_u64 v[210:211], v[146:147], 1, v[210:211]
	global_load_dwordx4 v[212:215], v[210:211], off
	global_load_dwordx4 v[216:219], v[210:211], off offset:256
	v_add_u32_e32 v220, 0x80, v144
	v_ashrrev_i32_e32 v221, 31, v220
	v_lshlrev_b64 v[220:221], 11, v[220:221]
	v_lshl_add_u64 v[220:221], s[10:11], 0, v[220:221]
	v_lshl_add_u64 v[220:221], v[146:147], 1, v[220:221]
	global_load_dwordx4 v[222:225], v[220:221], off
	global_load_dwordx4 v[226:229], v[220:221], off offset:256
	v_add_u32_e32 v230, 0x90, v144
	v_ashrrev_i32_e32 v231, 31, v230
	v_lshlrev_b64 v[230:231], 11, v[230:231]
	v_lshl_add_u64 v[230:231], s[10:11], 0, v[230:231]
	v_lshl_add_u64 v[230:231], v[146:147], 1, v[230:231]
	global_load_dwordx4 v[232:235], v[230:231], off
	global_load_dwordx4 v[236:239], v[230:231], off offset:256
	v_add_u32_e32 v240, 0xa0, v144
	v_ashrrev_i32_e32 v241, 31, v240
	v_lshlrev_b64 v[240:241], 11, v[240:241]
	v_lshl_add_u64 v[240:241], s[10:11], 0, v[240:241]
	v_lshl_add_u64 v[240:241], v[146:147], 1, v[240:241]
	global_load_dwordx4 v[242:245], v[240:241], off
	global_load_dwordx4 v[246:249], v[240:241], off offset:256
	v_cmp_eq_u32_e32 vcc, 0, v169
	s_waitcnt vmcnt(12)
	v_lshlrev_b32_e32 v180, 16, v170
	v_and_b32_e32 v181, 0xffff0000, v170
	v_lshlrev_b32_e32 v170, 16, v171
	v_and_b32_e32 v171, 0xffff0000, v171
	v_lshlrev_b32_e32 v182, 16, v172
	v_and_b32_e32 v183, 0xffff0000, v172
	v_lshlrev_b32_e32 v172, 16, v173
	v_and_b32_e32 v173, 0xffff0000, v173
	v_lshlrev_b32_e32 v184, 16, v174
	v_and_b32_e32 v185, 0xffff0000, v174
	v_lshlrev_b32_e32 v174, 16, v175
	v_and_b32_e32 v175, 0xffff0000, v175
	v_lshlrev_b32_e32 v186, 16, v176
	v_and_b32_e32 v187, 0xffff0000, v176
	v_lshlrev_b32_e32 v176, 16, v177
	v_and_b32_e32 v177, 0xffff0000, v177
	v_pk_add_f32 v[126:127], v[126:127], v[170:171]
	v_pk_add_f32 v[124:125], v[124:125], v[180:181]
	v_pk_add_f32 v[122:123], v[122:123], v[172:173]
	v_pk_add_f32 v[170:171], v[118:119], v[174:175]
	v_pk_add_f32 v[172:173], v[116:117], v[184:185]
	v_pk_add_f32 v[120:121], v[120:121], v[182:183]
	v_pk_add_f32 v[174:175], v[114:115], v[176:177]
	v_pk_add_f32 v[176:177], v[112:113], v[186:187]
	v_cvt_pk_bf16_f32 v112, v124, v125
	v_cvt_pk_bf16_f32 v113, v126, v127
	v_mul_f32_e32 v125, v125, v125
	v_mul_f32_e32 v127, v127, v127
	v_mul_f32_e32 v145, v173, v173
	v_mul_f32_e32 v169, v171, v171
	v_cvt_pk_bf16_f32 v114, v120, v121
	v_cvt_pk_bf16_f32 v115, v122, v123
	v_mul_f32_e32 v121, v121, v121
	v_cvt_pk_bf16_f32 v117, v170, v171
	v_mul_f32_e32 v171, v177, v177
	v_fmac_f32_e32 v125, v124, v124
	v_fmac_f32_e32 v127, v126, v126
	v_fmac_f32_e32 v145, v172, v172
	v_fmac_f32_e32 v169, v170, v170
	v_mul_f32_e32 v123, v123, v123
	v_cvt_pk_bf16_f32 v116, v172, v173
	v_mul_f32_e32 v173, v175, v175
	global_store_dwordx4 v[178:179], v[112:115], off
	v_fmac_f32_e32 v121, v120, v120
	v_fmac_f32_e32 v171, v176, v176
	v_add_f32_e32 v112, v125, v127
	v_add_f32_e32 v113, v145, v169
	v_fmac_f32_e32 v123, v122, v122
	v_fmac_f32_e32 v173, v174, v174
	v_add_f32_e32 v112, v121, v112
	v_add_f32_e32 v113, v171, v113
	v_add_f32_e32 v112, v123, v112
	v_add_f32_e32 v113, v173, v113
	v_add_f32_e32 v112, v112, v113
	v_mov_b32_e32 v113, v112
	s_nop 1
	v_permlane16_swap_b32_e32 v112, v113
	v_add_f32_e32 v113, v112, v113
	v_mov_b32_e32 v114, v113
	v_cvt_pk_bf16_f32 v118, v176, v177
	v_cvt_pk_bf16_f32 v119, v174, v175
	v_permlane32_swap_b32_e32 v113, v114
	v_lshl_add_u32 v112, v188, 4, s52
	global_store_dwordx4 v[178:179], v[116:119], off offset:256
	s_and_saveexec_b64 s[0:1], vcc
	v_add_f32_e32 v113, v113, v114
	ds_write_b32 v112, v113
	s_or_b64 exec, exec, s[0:1]
	s_waitcnt vmcnt(13)
	v_lshlrev_b32_e32 v124, 16, v192
	v_and_b32_e32 v125, 0xffff0000, v192
	v_lshlrev_b32_e32 v114, 16, v193
	v_and_b32_e32 v115, 0xffff0000, v193
	v_lshlrev_b32_e32 v126, 16, v194
	v_and_b32_e32 v127, 0xffff0000, v194
	v_lshlrev_b32_e32 v116, 16, v195
	v_and_b32_e32 v117, 0xffff0000, v195
	s_waitcnt vmcnt(12)
; __device__ __forceinline__ unsigned pk2(float lo, float hi) { f32x2_t v = {lo, hi}; bf16x2_t b = __builtin_convertvector(v, bf16x2_t); return __builtin_bit_cast(unsigned, b); }
; __device__ __forceinline__ float xor16_sum(float v) { const auto r = __builtin_amdgcn_permlane16_swap(__float_as_uint(v), __float_as_uint(v), false, false); return __uint_as_float(r[0]) + __uint_as_float(r[1]); }
; __device__ __forceinline__ float xor32_sum(float v) { const auto r = __builtin_amdgcn_permlane32_swap(__float_as_uint(v), __float_as_uint(v), false, false); return __uint_as_float(r[0]) + __uint_as_float(r[1]); }
; #define BF16_LO(w) __uint_as_float((w) << 16)
; #define BF16_HI(w) __uint_as_float((w) & 0xffff0000u)
;     __device__ __forceinline__ void operator()(const f32x4 (&acc)[2][2][4][2], const Unit& u, int wr, int wc, int fr_in, int fq_in) const {
;     ...
; #pragma unroll
;         for (int ai = 0; ai < 2; ++ai)
; #pragma unroll
;             for (int m = 0; m < 4; ++m) {
;                 const int row = u.pm * BM + ai * 128 + wr * 64 + m * 16 + fr;
;                 float s = 0.f;
; #pragma unroll
;                 for (int bj = 0; bj < 2; ++bj) {
;                     const size_t off = (size_t)row * DM + u.pn * BM + bj * HALF + wc * 32 + 8 * fq;
;                     f32x4 b0, b1;
;                     if (xbase) { b0 = *(const f32x4*)(xbase + off); b1 = *(const f32x4*)(xbase + off + 4); }
;                     else { const u32x4 q = *(const u32x4*)(hb + off);
;                         b0 = (f32x4){BF16_LO(q.x), BF16_HI(q.x), BF16_LO(q.y), BF16_HI(q.y)}; b1 = (f32x4){BF16_LO(q.z), BF16_HI(q.z), BF16_LO(q.w), BF16_HI(q.w)}; }
;                     const f32x4 h0 = b0 + acc[ai][bj][m][0], h1 = b1 + acc[ai][bj][m][1];
;                     u32x4 w; w.x = pk2(h0[0], h0[1]); w.y = pk2(h0[2], h0[3]); w.z = pk2(h1[0], h1[1]); w.w = pk2(h1[2], h1[3]);
;                     *(u32x4*)(hb + off) = w;
;                     s += (h0[0] * h0[0] + h0[1] * h0[1]) + (h0[2] * h0[2] + h0[3] * h0[3]) + (h1[0] * h1[0] + h1[1] * h1[1]) + (h1[2] * h1[2] + h1[3] * h1[3]);
;                 }
;                 s = xor32_sum(xor16_sum(s));
;                 if (fq == 0) xch[(ai * 128 + wr * 64 + m * 16 + fr) * 4 + wc] = s;
;                 if (m == 3) asm volatile("" ::: "memory");
	v_lshlrev_b32_e32 v170, 16, v196
	v_and_b32_e32 v171, 0xffff0000, v196
	v_lshlrev_b32_e32 v118, 16, v197
	v_and_b32_e32 v119, 0xffff0000, v197
	v_lshlrev_b32_e32 v172, 16, v198
	v_and_b32_e32 v173, 0xffff0000, v198
	v_lshlrev_b32_e32 v120, 16, v199
	v_and_b32_e32 v121, 0xffff0000, v199
	v_pk_add_f32 v[110:111], v[110:111], v[114:115]
	v_pk_add_f32 v[108:109], v[108:109], v[124:125]
	v_pk_add_f32 v[106:107], v[106:107], v[116:117]
	v_pk_add_f32 v[114:115], v[102:103], v[118:119]
	v_pk_add_f32 v[116:117], v[100:101], v[170:171]
	v_pk_add_f32 v[104:105], v[104:105], v[126:127]
	v_pk_add_f32 v[118:119], v[98:99], v[120:121]
	v_pk_add_f32 v[120:121], v[96:97], v[172:173]
	v_cvt_pk_bf16_f32 v96, v108, v109
	v_cvt_pk_bf16_f32 v97, v110, v111
	v_mul_f32_e32 v109, v109, v109
	v_mul_f32_e32 v111, v111, v111
	v_cvt_pk_bf16_f32 v101, v114, v115
	v_mul_f32_e32 v113, v117, v117
	v_mul_f32_e32 v115, v115, v115
	v_cvt_pk_bf16_f32 v98, v104, v105
	v_cvt_pk_bf16_f32 v99, v106, v107
	v_mul_f32_e32 v105, v105, v105
	v_cvt_pk_bf16_f32 v100, v116, v117
	v_mul_f32_e32 v117, v121, v121
	v_fmac_f32_e32 v109, v108, v108
	v_fmac_f32_e32 v111, v110, v110
	v_fmac_f32_e32 v113, v116, v116
	v_fmac_f32_e32 v115, v114, v114
	v_mul_f32_e32 v107, v107, v107
	v_cvt_pk_bf16_f32 v103, v118, v119
	v_mul_f32_e32 v119, v119, v119
	global_store_dwordx4 v[190:191], v[96:99], off
	v_fmac_f32_e32 v105, v104, v104
	v_fmac_f32_e32 v117, v120, v120
	v_add_f32_e32 v96, v109, v111
	v_add_f32_e32 v97, v113, v115
	v_fmac_f32_e32 v107, v106, v106
	v_fmac_f32_e32 v119, v118, v118
	v_add_f32_e32 v96, v105, v96
	v_add_f32_e32 v97, v117, v97
	v_add_f32_e32 v96, v107, v96
	v_add_f32_e32 v97, v119, v97
	v_add_f32_e32 v96, v96, v97
	v_mov_b32_e32 v97, v96
	s_nop 1
	v_permlane16_swap_b32_e32 v96, v97
	v_add_f32_e32 v96, v96, v97
	v_mov_b32_e32 v97, v96
	v_cvt_pk_bf16_f32 v102, v120, v121
	s_nop 0
	v_permlane32_swap_b32_e32 v96, v97
	global_store_dwordx4 v[190:191], v[100:103], off offset:256
	s_and_saveexec_b64 s[0:1], vcc
	v_add_f32_e32 v96, v96, v97
	ds_write_b32 v112, v96 offset:256
	s_or_b64 exec, exec, s[0:1]
	s_waitcnt vmcnt(13)
	v_lshlrev_b32_e32 v106, 16, v202
	v_and_b32_e32 v107, 0xffff0000, v202
	v_lshlrev_b32_e32 v96, 16, v203
	v_and_b32_e32 v97, 0xffff0000, v203
	v_lshlrev_b32_e32 v108, 16, v204
	v_and_b32_e32 v109, 0xffff0000, v204
	v_lshlrev_b32_e32 v98, 16, v205
	v_and_b32_e32 v99, 0xffff0000, v205
	s_waitcnt vmcnt(12)
	v_lshlrev_b32_e32 v110, 16, v206
	v_and_b32_e32 v111, 0xffff0000, v206
	v_lshlrev_b32_e32 v100, 16, v207
	v_and_b32_e32 v101, 0xffff0000, v207
	v_lshlrev_b32_e32 v114, 16, v208
	v_and_b32_e32 v115, 0xffff0000, v208
	v_lshlrev_b32_e32 v102, 16, v209
	v_and_b32_e32 v103, 0xffff0000, v209
	v_pk_add_f32 v[94:95], v[94:95], v[96:97]
	v_pk_add_f32 v[92:93], v[92:93], v[106:107]
	v_pk_add_f32 v[90:91], v[90:91], v[98:99]
	v_pk_add_f32 v[96:97], v[86:87], v[100:101]
	v_pk_add_f32 v[98:99], v[84:85], v[110:111]
	v_pk_add_f32 v[88:89], v[88:89], v[108:109]
	v_pk_add_f32 v[100:101], v[82:83], v[102:103]
	v_pk_add_f32 v[102:103], v[80:81], v[114:115]
	v_cvt_pk_bf16_f32 v80, v92, v93
	v_cvt_pk_bf16_f32 v81, v94, v95
	v_mul_f32_e32 v93, v93, v93
	v_mul_f32_e32 v95, v95, v95
	v_cvt_pk_bf16_f32 v84, v98, v99
	v_cvt_pk_bf16_f32 v85, v96, v97
	v_mul_f32_e32 v99, v99, v99
	v_mul_f32_e32 v97, v97, v97
	v_cvt_pk_bf16_f32 v82, v88, v89
	v_cvt_pk_bf16_f32 v83, v90, v91
	v_mul_f32_e32 v89, v89, v89
	v_cvt_pk_bf16_f32 v86, v102, v103
	v_mul_f32_e32 v103, v103, v103
	v_fmac_f32_e32 v93, v92, v92
	v_fmac_f32_e32 v95, v94, v94
	v_fmac_f32_e32 v99, v98, v98
	v_fmac_f32_e32 v97, v96, v96
	v_mul_f32_e32 v91, v91, v91
	v_cvt_pk_bf16_f32 v87, v100, v101
	v_mul_f32_e32 v101, v101, v101
	global_store_dwordx4 v[200:201], v[80:83], off
	v_fmac_f32_e32 v89, v88, v88
	v_fmac_f32_e32 v103, v102, v102
	v_add_f32_e32 v80, v93, v95
	v_add_f32_e32 v81, v99, v97
	v_fmac_f32_e32 v91, v90, v90
	v_fmac_f32_e32 v101, v100, v100
	v_add_f32_e32 v80, v89, v80
	v_add_f32_e32 v81, v103, v81
	v_add_f32_e32 v80, v91, v80
	v_add_f32_e32 v81, v101, v81
	v_add_f32_e32 v80, v80, v81
	v_mov_b32_e32 v81, v80
	s_nop 1
	v_permlane16_swap_b32_e32 v80, v81
	v_add_f32_e32 v80, v80, v81
	v_mov_b32_e32 v81, v80
	s_nop 1
	v_permlane32_swap_b32_e32 v80, v81
	global_store_dwordx4 v[200:201], v[84:87], off offset:256
	s_and_saveexec_b64 s[0:1], vcc
	v_add_f32_e32 v80, v80, v81
	ds_write_b32 v112, v80 offset:512
	s_or_b64 exec, exec, s[0:1]
	s_waitcnt vmcnt(13)
	v_lshlrev_b32_e32 v90, 16, v212
	v_and_b32_e32 v91, 0xffff0000, v212
	v_lshlrev_b32_e32 v80, 16, v213
	v_and_b32_e32 v81, 0xffff0000, v213
	v_lshlrev_b32_e32 v92, 16, v214
	v_and_b32_e32 v93, 0xffff0000, v214
	v_lshlrev_b32_e32 v82, 16, v215
	v_and_b32_e32 v83, 0xffff0000, v215
	s_waitcnt vmcnt(12)
; __device__ __forceinline__ unsigned pk2(float lo, float hi) { f32x2_t v = {lo, hi}; bf16x2_t b = __builtin_convertvector(v, bf16x2_t); return __builtin_bit_cast(unsigned, b); }
; __device__ __forceinline__ float xor16_sum(float v) { const auto r = __builtin_amdgcn_permlane16_swap(__float_as_uint(v), __float_as_uint(v), false, false); return __uint_as_float(r[0]) + __uint_as_float(r[1]); }
; __device__ __forceinline__ float xor32_sum(float v) { const auto r = __builtin_amdgcn_permlane32_swap(__float_as_uint(v), __float_as_uint(v), false, false); return __uint_as_float(r[0]) + __uint_as_float(r[1]); }
; #define BF16_LO(w) __uint_as_float((w) << 16)
; #define BF16_HI(w) __uint_as_float((w) & 0xffff0000u)
;     __device__ __forceinline__ void operator()(const f32x4 (&acc)[2][2][4][2], const Unit& u, int wr, int wc, int fr_in, int fq_in) const {
;     ...
; #pragma unroll
;         for (int ai = 0; ai < 2; ++ai)
; #pragma unroll
;             for (int m = 0; m < 4; ++m) {
;                 const int row = u.pm * BM + ai * 128 + wr * 64 + m * 16 + fr;
;                 float s = 0.f;
; #pragma unroll
;                 for (int bj = 0; bj < 2; ++bj) {
;                     const size_t off = (size_t)row * DM + u.pn * BM + bj * HALF + wc * 32 + 8 * fq;
;                     f32x4 b0, b1;
;                     if (xbase) { b0 = *(const f32x4*)(xbase + off); b1 = *(const f32x4*)(xbase + off + 4); }
;                     else { const u32x4 q = *(const u32x4*)(hb + off);
;                         b0 = (f32x4){BF16_LO(q.x), BF16_HI(q.x), BF16_LO(q.y), BF16_HI(q.y)}; b1 = (f32x4){BF16_LO(q.z), BF16_HI(q.z), BF16_LO(q.w), BF16_HI(q.w)}; }
;                     const f32x4 h0 = b0 + acc[ai][bj][m][0], h1 = b1 + acc[ai][bj][m][1];
;                     u32x4 w; w.x = pk2(h0[0], h0[1]); w.y = pk2(h0[2], h0[3]); w.z = pk2(h1[0], h1[1]); w.w = pk2(h1[2], h1[3]);
;                     *(u32x4*)(hb + off) = w;
;                     s += (h0[0] * h0[0] + h0[1] * h0[1]) + (h0[2] * h0[2] + h0[3] * h0[3]) + (h1[0] * h1[0] + h1[1] * h1[1]) + (h1[2] * h1[2] + h1[3] * h1[3]);
;                 }
;                 s = xor32_sum(xor16_sum(s));
;                 if (fq == 0) xch[(ai * 128 + wr * 64 + m * 16 + fr) * 4 + wc] = s;
;                 if (m == 3) asm volatile("" ::: "memory");
	v_lshlrev_b32_e32 v94, 16, v216
	v_and_b32_e32 v95, 0xffff0000, v216
	v_lshlrev_b32_e32 v84, 16, v217
	v_and_b32_e32 v85, 0xffff0000, v217
	v_lshlrev_b32_e32 v96, 16, v218
	v_and_b32_e32 v97, 0xffff0000, v218
	v_lshlrev_b32_e32 v86, 16, v219
	v_and_b32_e32 v87, 0xffff0000, v219
	v_pk_add_f32 v[78:79], v[78:79], v[80:81]
	v_pk_add_f32 v[76:77], v[76:77], v[90:91]
	v_pk_add_f32 v[74:75], v[74:75], v[82:83]
	v_pk_add_f32 v[80:81], v[70:71], v[84:85]
	v_pk_add_f32 v[82:83], v[68:69], v[94:95]
	v_pk_add_f32 v[72:73], v[72:73], v[92:93]
	v_pk_add_f32 v[84:85], v[66:67], v[86:87]
	v_pk_add_f32 v[86:87], v[64:65], v[96:97]
	v_cvt_pk_bf16_f32 v64, v76, v77
	v_cvt_pk_bf16_f32 v65, v78, v79
	v_mul_f32_e32 v77, v77, v77
	v_mul_f32_e32 v79, v79, v79
	v_cvt_pk_bf16_f32 v68, v82, v83
	v_cvt_pk_bf16_f32 v69, v80, v81
	v_mul_f32_e32 v83, v83, v83
	v_mul_f32_e32 v81, v81, v81
	v_cvt_pk_bf16_f32 v66, v72, v73
	v_cvt_pk_bf16_f32 v67, v74, v75
	v_mul_f32_e32 v73, v73, v73
	v_cvt_pk_bf16_f32 v70, v86, v87
	v_mul_f32_e32 v87, v87, v87
	v_fmac_f32_e32 v77, v76, v76
	v_fmac_f32_e32 v79, v78, v78
	v_fmac_f32_e32 v83, v82, v82
	v_fmac_f32_e32 v81, v80, v80
	v_mul_f32_e32 v75, v75, v75
	v_cvt_pk_bf16_f32 v71, v84, v85
	v_mul_f32_e32 v85, v85, v85
	global_store_dwordx4 v[210:211], v[64:67], off
	v_fmac_f32_e32 v73, v72, v72
	v_fmac_f32_e32 v87, v86, v86
	v_add_f32_e32 v64, v77, v79
	v_add_f32_e32 v65, v83, v81
	v_fmac_f32_e32 v75, v74, v74
	v_fmac_f32_e32 v85, v84, v84
	v_add_f32_e32 v64, v73, v64
	v_add_f32_e32 v65, v87, v65
	v_add_f32_e32 v64, v75, v64
	v_add_f32_e32 v65, v85, v65
	v_add_f32_e32 v64, v64, v65
	v_mov_b32_e32 v65, v64
	s_nop 1
	v_permlane16_swap_b32_e32 v64, v65
	v_add_f32_e32 v64, v64, v65
	v_mov_b32_e32 v65, v64
	s_nop 1
	v_permlane32_swap_b32_e32 v64, v65
	global_store_dwordx4 v[210:211], v[68:71], off offset:256
	s_and_saveexec_b64 s[0:1], vcc
	v_add_f32_e32 v64, v64, v65
	ds_write_b32 v112, v64 offset:768
	s_or_b64 exec, exec, s[0:1]
	s_waitcnt vmcnt(13)
	v_lshlrev_b32_e32 v74, 16, v222
	v_and_b32_e32 v75, 0xffff0000, v222
	v_lshlrev_b32_e32 v64, 16, v223
	v_and_b32_e32 v65, 0xffff0000, v223
	v_lshlrev_b32_e32 v76, 16, v224
	v_and_b32_e32 v77, 0xffff0000, v224
	v_lshlrev_b32_e32 v66, 16, v225
	v_and_b32_e32 v67, 0xffff0000, v225
	s_waitcnt vmcnt(12)
	v_lshlrev_b32_e32 v78, 16, v226
	v_and_b32_e32 v79, 0xffff0000, v226
	v_lshlrev_b32_e32 v68, 16, v227
	v_and_b32_e32 v69, 0xffff0000, v227
	v_lshlrev_b32_e32 v80, 16, v228
	v_and_b32_e32 v81, 0xffff0000, v228
	v_lshlrev_b32_e32 v70, 16, v229
	v_and_b32_e32 v71, 0xffff0000, v229
	v_pk_add_f32 v[62:63], v[62:63], v[64:65]
	v_pk_add_f32 v[60:61], v[60:61], v[74:75]
	v_pk_add_f32 v[58:59], v[58:59], v[66:67]
	v_pk_add_f32 v[64:65], v[54:55], v[68:69]
	v_pk_add_f32 v[66:67], v[52:53], v[78:79]
	v_pk_add_f32 v[56:57], v[56:57], v[76:77]
	v_pk_add_f32 v[68:69], v[50:51], v[70:71]
	v_pk_add_f32 v[70:71], v[48:49], v[80:81]
	v_cvt_pk_bf16_f32 v48, v60, v61
	v_cvt_pk_bf16_f32 v49, v62, v63
	v_mul_f32_e32 v61, v61, v61
	v_mul_f32_e32 v63, v63, v63
	v_cvt_pk_bf16_f32 v52, v66, v67
	v_cvt_pk_bf16_f32 v53, v64, v65
	v_mul_f32_e32 v67, v67, v67
	v_mul_f32_e32 v65, v65, v65
	v_cvt_pk_bf16_f32 v50, v56, v57
	v_cvt_pk_bf16_f32 v51, v58, v59
	v_mul_f32_e32 v57, v57, v57
	v_cvt_pk_bf16_f32 v54, v70, v71
	v_mul_f32_e32 v71, v71, v71
	v_fmac_f32_e32 v61, v60, v60
	v_fmac_f32_e32 v63, v62, v62
	v_fmac_f32_e32 v67, v66, v66
	v_fmac_f32_e32 v65, v64, v64
	v_mul_f32_e32 v59, v59, v59
	v_cvt_pk_bf16_f32 v55, v68, v69
	v_mul_f32_e32 v69, v69, v69
	global_store_dwordx4 v[220:221], v[48:51], off
	v_fmac_f32_e32 v57, v56, v56
	v_fmac_f32_e32 v71, v70, v70
	v_add_f32_e32 v48, v61, v63
	v_add_f32_e32 v49, v67, v65
	v_fmac_f32_e32 v59, v58, v58
	v_fmac_f32_e32 v69, v68, v68
	v_add_f32_e32 v48, v57, v48
	v_add_f32_e32 v49, v71, v49
	v_add_f32_e32 v48, v59, v48
	v_add_f32_e32 v49, v69, v49
	v_add_f32_e32 v48, v48, v49
	v_mov_b32_e32 v49, v48
	s_nop 1
	v_permlane16_swap_b32_e32 v48, v49
	v_add_f32_e32 v48, v48, v49
	v_mov_b32_e32 v49, v48
	s_nop 1
	v_permlane32_swap_b32_e32 v48, v49
	global_store_dwordx4 v[220:221], v[52:55], off offset:256
	s_and_saveexec_b64 s[0:1], vcc
	v_add_f32_e32 v48, v48, v49
	ds_write_b32 v112, v48 offset:2048
	s_or_b64 exec, exec, s[0:1]
	s_waitcnt vmcnt(13)
	v_lshlrev_b32_e32 v58, 16, v232
	v_and_b32_e32 v59, 0xffff0000, v232
	v_lshlrev_b32_e32 v48, 16, v233
	v_and_b32_e32 v49, 0xffff0000, v233
	v_lshlrev_b32_e32 v60, 16, v234
	v_and_b32_e32 v61, 0xffff0000, v234
	v_lshlrev_b32_e32 v50, 16, v235
	v_and_b32_e32 v51, 0xffff0000, v235
	s_waitcnt vmcnt(12)
	v_lshlrev_b32_e32 v62, 16, v236
	v_and_b32_e32 v63, 0xffff0000, v236
	v_lshlrev_b32_e32 v52, 16, v237
	v_and_b32_e32 v53, 0xffff0000, v237
	v_lshlrev_b32_e32 v64, 16, v238
	v_and_b32_e32 v65, 0xffff0000, v238
	v_lshlrev_b32_e32 v54, 16, v239
	v_and_b32_e32 v55, 0xffff0000, v239
	v_pk_add_f32 v[46:47], v[46:47], v[48:49]
	v_pk_add_f32 v[44:45], v[44:45], v[58:59]
	v_pk_add_f32 v[42:43], v[42:43], v[50:51]
	v_pk_add_f32 v[48:49], v[38:39], v[52:53]
	v_pk_add_f32 v[50:51], v[36:37], v[62:63]
	v_pk_add_f32 v[40:41], v[40:41], v[60:61]
	v_pk_add_f32 v[52:53], v[34:35], v[54:55]
	v_pk_add_f32 v[54:55], v[32:33], v[64:65]
	v_cvt_pk_bf16_f32 v32, v44, v45
	v_cvt_pk_bf16_f32 v33, v46, v47
	v_mul_f32_e32 v45, v45, v45
	v_mul_f32_e32 v47, v47, v47
	v_cvt_pk_bf16_f32 v36, v50, v51
	v_cvt_pk_bf16_f32 v37, v48, v49
	v_mul_f32_e32 v51, v51, v51
	v_mul_f32_e32 v49, v49, v49
	v_cvt_pk_bf16_f32 v34, v40, v41
	v_cvt_pk_bf16_f32 v35, v42, v43
	v_mul_f32_e32 v41, v41, v41
	v_cvt_pk_bf16_f32 v38, v54, v55
	v_mul_f32_e32 v55, v55, v55
	v_fmac_f32_e32 v45, v44, v44
	v_fmac_f32_e32 v47, v46, v46
	v_fmac_f32_e32 v51, v50, v50
	v_fmac_f32_e32 v49, v48, v48
	v_mul_f32_e32 v43, v43, v43
	v_cvt_pk_bf16_f32 v39, v52, v53
	v_mul_f32_e32 v53, v53, v53
	global_store_dwordx4 v[230:231], v[32:35], off
	v_fmac_f32_e32 v41, v40, v40
	v_fmac_f32_e32 v55, v54, v54
	v_add_f32_e32 v32, v45, v47
	v_add_f32_e32 v33, v51, v49
	v_fmac_f32_e32 v43, v42, v42
	v_fmac_f32_e32 v53, v52, v52
	v_add_f32_e32 v32, v41, v32
	v_add_f32_e32 v33, v55, v33
	v_add_f32_e32 v32, v43, v32
	v_add_f32_e32 v33, v53, v33
	v_add_f32_e32 v32, v32, v33
	v_mov_b32_e32 v33, v32
	s_nop 1
	v_permlane16_swap_b32_e32 v32, v33
	v_add_f32_e32 v32, v32, v33
	v_mov_b32_e32 v33, v32
	s_nop 1
	v_permlane32_swap_b32_e32 v32, v33
	global_store_dwordx4 v[230:231], v[36:39], off offset:256
	s_and_saveexec_b64 s[0:1], vcc
	v_add_f32_e32 v32, v32, v33
	ds_write_b32 v112, v32 offset:2304
	s_or_b64 exec, exec, s[0:1]
	s_waitcnt vmcnt(13)
; __device__ __forceinline__ unsigned pk2(float lo, float hi) { f32x2_t v = {lo, hi}; bf16x2_t b = __builtin_convertvector(v, bf16x2_t); return __builtin_bit_cast(unsigned, b); }
; __device__ __forceinline__ float xor16_sum(float v) { const auto r = __builtin_amdgcn_permlane16_swap(__float_as_uint(v), __float_as_uint(v), false, false); return __uint_as_float(r[0]) + __uint_as_float(r[1]); }
;     __device__ __forceinline__ void operator()(const f32x4 (&acc)[2][2][4][2], const Unit& u, int wr, int wc, int fr_in, int fq_in) const {
;     ...
; #pragma unroll
;         for (int ai = 0; ai < 2; ++ai)
; #pragma unroll
;             for (int m = 0; m < 4; ++m) {
;                 const int row = u.pm * BM + ai * 128 + wr * 64 + m * 16 + fr;
;                 float s = 0.f;
; #pragma unroll
;                 for (int bj = 0; bj < 2; ++bj) {
;                     const size_t off = (size_t)row * DM + u.pn * BM + bj * HALF + wc * 32 + 8 * fq;
;                     f32x4 b0, b1;
;                     if (xbase) { b0 = *(const f32x4*)(xbase + off); b1 = *(const f32x4*)(xbase + off + 4); }
;                     else { const u32x4 q = *(const u32x4*)(hb + off);
;                         b0 = (f32x4){BF16_LO(q.x), BF16_HI(q.x), BF16_LO(q.y), BF16_HI(q.y)}; b1 = (f32x4){BF16_LO(q.z), BF16_HI(q.z), BF16_LO(q.w), BF16_HI(q.w)}; }
;                     const f32x4 h0 = b0 + acc[ai][bj][m][0], h1 = b1 + acc[ai][bj][m][1];
;                     u32x4 w; w.x = pk2(h0[0], h0[1]); w.y = pk2(h0[2], h0[3]); w.z = pk2(h1[0], h1[1]); w.w = pk2(h1[2], h1[3]);
;                     *(u32x4*)(hb + off) = w;
;                     s += (h0[0] * h0[0] + h0[1] * h0[1]) + (h0[2] * h0[2] + h0[3] * h0[3]) + (h1[0] * h1[0] + h1[1] * h1[1]) + (h1[2] * h1[2] + h1[3] * h1[3]);
;                 }
;                 s = xor32_sum(xor16_sum(s));
;                 if (fq == 0) xch[(ai * 128 + wr * 64 + m * 16 + fr) * 4 + wc] = s;
;                 if (m == 3) asm volatile("" ::: "memory");
;             }
;         PG8_EPI_BAR();
;         if (fq == 0) {
; #pragma unroll
;             for (int ai = 0; ai < 2; ++ai) {
;                 const int rl = ai * 128 + wr * 64 + wc * 16 + fr;
;                 const f32x4 p = *(const PG8_LAS f32x4*)(xch + rl * 4);
;                 const float t = (p[0] + p[1]) + (p[2] + p[3]);
;                 atomicAdd(rsq + u.pm * BM + rl, (u64_t)(t * 16777216.0f));
;             }
	v_lshlrev_b32_e32 v42, 16, v242
	v_and_b32_e32 v43, 0xffff0000, v242
	v_lshlrev_b32_e32 v32, 16, v243
	v_and_b32_e32 v33, 0xffff0000, v243
	v_lshlrev_b32_e32 v44, 16, v244
	v_and_b32_e32 v45, 0xffff0000, v244
	v_lshlrev_b32_e32 v34, 16, v245
	v_and_b32_e32 v35, 0xffff0000, v245
	s_waitcnt vmcnt(12)
	v_lshlrev_b32_e32 v46, 16, v246
	v_and_b32_e32 v47, 0xffff0000, v246
	v_lshlrev_b32_e32 v36, 16, v247
	v_and_b32_e32 v37, 0xffff0000, v247
	v_lshlrev_b32_e32 v48, 16, v248
	v_and_b32_e32 v49, 0xffff0000, v248
	v_lshlrev_b32_e32 v38, 16, v249
	v_and_b32_e32 v39, 0xffff0000, v249
	v_pk_add_f32 v[30:31], v[30:31], v[32:33]
	v_pk_add_f32 v[28:29], v[28:29], v[42:43]
	v_pk_add_f32 v[26:27], v[26:27], v[34:35]
	v_pk_add_f32 v[32:33], v[22:23], v[36:37]
	v_pk_add_f32 v[34:35], v[20:21], v[46:47]
	v_pk_add_f32 v[24:25], v[24:25], v[44:45]
	v_pk_add_f32 v[36:37], v[18:19], v[38:39]
	v_pk_add_f32 v[38:39], v[16:17], v[48:49]
	v_cvt_pk_bf16_f32 v16, v28, v29
	v_cvt_pk_bf16_f32 v17, v30, v31
	v_mul_f32_e32 v29, v29, v29
	v_mul_f32_e32 v31, v31, v31
	v_cvt_pk_bf16_f32 v20, v34, v35
	v_cvt_pk_bf16_f32 v21, v32, v33
	v_mul_f32_e32 v35, v35, v35
	v_mul_f32_e32 v33, v33, v33
	v_cvt_pk_bf16_f32 v18, v24, v25
	v_cvt_pk_bf16_f32 v19, v26, v27
	v_mul_f32_e32 v25, v25, v25
	v_cvt_pk_bf16_f32 v22, v38, v39
	v_mul_f32_e32 v39, v39, v39
	v_fmac_f32_e32 v29, v28, v28
	v_fmac_f32_e32 v31, v30, v30
	v_fmac_f32_e32 v35, v34, v34
	v_fmac_f32_e32 v33, v32, v32
	v_mul_f32_e32 v27, v27, v27
	v_cvt_pk_bf16_f32 v23, v36, v37
	v_mul_f32_e32 v37, v37, v37
	global_store_dwordx4 v[240:241], v[16:19], off
	v_fmac_f32_e32 v25, v24, v24
	v_fmac_f32_e32 v39, v38, v38
	v_add_f32_e32 v16, v29, v31
	v_add_f32_e32 v17, v35, v33
	v_fmac_f32_e32 v27, v26, v26
	v_fmac_f32_e32 v37, v36, v36
	v_add_f32_e32 v16, v25, v16
	v_add_f32_e32 v17, v39, v17
	v_add_f32_e32 v16, v27, v16
	v_add_f32_e32 v17, v37, v17
	v_add_f32_e32 v16, v16, v17
	v_mov_b32_e32 v17, v16
	s_nop 1
	v_permlane16_swap_b32_e32 v16, v17
	v_add_f32_e32 v16, v16, v17
	v_mov_b32_e32 v17, v16
	s_nop 1
	v_permlane32_swap_b32_e32 v16, v17
	global_store_dwordx4 v[240:241], v[20:23], off offset:256
	s_and_saveexec_b64 s[0:1], vcc
	v_add_f32_e32 v16, v16, v17
	ds_write_b32 v112, v16 offset:2560
	s_or_b64 exec, exec, s[0:1]
	v_add_u32_e32 v16, 0xb0, v144
	v_ashrrev_i32_e32 v17, 31, v16
	v_lshlrev_b64 v[16:17], 11, v[16:17]
	v_lshl_add_u64 v[16:17], s[10:11], 0, v[16:17]
	v_lshl_add_u64 v[24:25], v[146:147], 1, v[16:17]
	global_load_dwordx4 v[16:19], v[24:25], off
	global_load_dwordx4 v[20:23], v[24:25], off offset:256
	s_waitcnt vmcnt(1)
	v_lshlrev_b32_e32 v26, 16, v16
	v_and_b32_e32 v27, 0xffff0000, v16
	v_lshlrev_b32_e32 v16, 16, v17
	v_and_b32_e32 v17, 0xffff0000, v17
	v_lshlrev_b32_e32 v28, 16, v18
	v_and_b32_e32 v29, 0xffff0000, v18
	v_lshlrev_b32_e32 v18, 16, v19
	v_and_b32_e32 v19, 0xffff0000, v19
	s_waitcnt vmcnt(0)
	v_lshlrev_b32_e32 v30, 16, v20
	v_and_b32_e32 v31, 0xffff0000, v20
	v_lshlrev_b32_e32 v20, 16, v21
	v_and_b32_e32 v21, 0xffff0000, v21
	v_lshlrev_b32_e32 v32, 16, v22
	v_and_b32_e32 v33, 0xffff0000, v22
	v_lshlrev_b32_e32 v22, 16, v23
	v_and_b32_e32 v23, 0xffff0000, v23
	v_pk_add_f32 v[14:15], v[14:15], v[16:17]
	v_pk_add_f32 v[12:13], v[12:13], v[26:27]
	v_pk_add_f32 v[10:11], v[10:11], v[18:19]
	v_pk_add_f32 v[16:17], v[6:7], v[20:21]
	v_pk_add_f32 v[18:19], v[4:5], v[30:31]
	v_pk_add_f32 v[8:9], v[8:9], v[28:29]
	v_pk_add_f32 v[20:21], v[2:3], v[22:23]
	v_pk_add_f32 v[22:23], v[0:1], v[32:33]
	v_cvt_pk_bf16_f32 v0, v12, v13
	v_cvt_pk_bf16_f32 v1, v14, v15
	v_mul_f32_e32 v13, v13, v13
	v_mul_f32_e32 v15, v15, v15
	v_cvt_pk_bf16_f32 v4, v18, v19
	v_cvt_pk_bf16_f32 v5, v16, v17
	v_mul_f32_e32 v19, v19, v19
	v_mul_f32_e32 v17, v17, v17
	v_cvt_pk_bf16_f32 v2, v8, v9
	v_cvt_pk_bf16_f32 v3, v10, v11
	v_mul_f32_e32 v9, v9, v9
	v_cvt_pk_bf16_f32 v6, v22, v23
	v_mul_f32_e32 v23, v23, v23
	v_fmac_f32_e32 v13, v12, v12
	v_fmac_f32_e32 v15, v14, v14
	v_fmac_f32_e32 v19, v18, v18
	v_fmac_f32_e32 v17, v16, v16
	v_mul_f32_e32 v11, v11, v11
	v_cvt_pk_bf16_f32 v7, v20, v21
	v_mul_f32_e32 v21, v21, v21
	global_store_dwordx4 v[24:25], v[0:3], off
	v_fmac_f32_e32 v9, v8, v8
	v_fmac_f32_e32 v23, v22, v22
	v_add_f32_e32 v0, v13, v15
	v_add_f32_e32 v1, v19, v17
	v_fmac_f32_e32 v11, v10, v10
	v_fmac_f32_e32 v21, v20, v20
	v_add_f32_e32 v0, v9, v0
	v_add_f32_e32 v1, v23, v1
	v_add_f32_e32 v0, v11, v0
	v_add_f32_e32 v1, v21, v1
	v_add_f32_e32 v0, v0, v1
	v_mov_b32_e32 v1, v0
	s_nop 1
	v_permlane16_swap_b32_e32 v0, v1
	v_add_f32_e32 v0, v0, v1
	v_mov_b32_e32 v1, v0
	s_nop 1
	v_permlane32_swap_b32_e32 v0, v1
	global_store_dwordx4 v[24:25], v[4:7], off offset:256
	s_and_saveexec_b64 s[0:1], vcc
	v_add_f32_e32 v0, v0, v1
	ds_write_b32 v112, v0 offset:2816
	s_or_b64 exec, exec, s[0:1]
	s_waitcnt lgkmcnt(0)
	s_barrier
	s_and_saveexec_b64 s[0:1], vcc
	s_cbranch_execz .LBB0_1480
	v_add_u32_e32 v4, s51, v168
	v_lshl_add_u32 v6, v4, 4, v167
	ds_read_b128 v[0:3], v6
	s_ashr_i32 s27, s26, 31
	s_lshl_b64 s[26:27], s[26:27], 3
	s_add_u32 s26, s42, s26
	s_addc_u32 s27, s43, s27
	s_waitcnt lgkmcnt(0)
	v_add_f32_e32 v0, v0, v1
	v_add_f32_e32 v1, v2, v3
	v_add_f32_e32 v0, v0, v1
	v_mul_f32_e32 v0, 0x4b800000, v0
	v_trunc_f32_e32 v0, v0
	v_mul_f32_e32 v1, 0x2f800000, v0
	v_floor_f32_e32 v1, v1
	v_fmac_f32_e32 v0, 0xcf800000, v1
	v_cvt_u32_f32_e32 v0, v0
	v_cvt_u32_f32_e32 v1, v1
	v_ashrrev_i32_e32 v5, 31, v4
	v_lshl_add_u64 v[4:5], v[4:5], 3, s[26:27]
	global_atomic_add_x2 v[4:5], v[0:1], off
	ds_read_b128 v[0:3], v6 offset:2048
	s_waitcnt lgkmcnt(0)
	v_add_f32_e32 v0, v0, v1
	v_add_f32_e32 v1, v2, v3
	v_add_f32_e32 v0, v0, v1
	v_mul_f32_e32 v0, 0x4b800000, v0
	v_trunc_f32_e32 v0, v0
	v_mul_f32_e32 v1, 0x2f800000, v0
	v_floor_f32_e32 v1, v1
	v_fmac_f32_e32 v0, 0xcf800000, v1
	v_cvt_u32_f32_e32 v0, v0
	v_cvt_u32_f32_e32 v1, v1
	global_atomic_add_x2 v[4:5], v[0:1], off offset:1024

; __device__ __forceinline__ unsigned pk2(float lo, float hi) { f32x2_t v = {lo, hi}; bf16x2_t b = __builtin_convertvector(v, bf16x2_t); return __builtin_bit_cast(unsigned, b); }
; __device__ __forceinline__ float xor16_sum(float v) { const auto r = __builtin_amdgcn_permlane16_swap(__float_as_uint(v), __float_as_uint(v), false, false); return __uint_as_float(r[0]) + __uint_as_float(r[1]); }
; __device__ __forceinline__ float xor32_sum(float v) { const auto r = __builtin_amdgcn_permlane32_swap(__float_as_uint(v), __float_as_uint(v), false, false); return __uint_as_float(r[0]) + __uint_as_float(r[1]); }
; #define BF16_LO(w) __uint_as_float((w) << 16)
; #define BF16_HI(w) __uint_as_float((w) & 0xffff0000u)
;     __device__ __forceinline__ void operator()(const f32x4 (&acc)[2][2][4][2], const Unit& u, int wr, int wc, int fr_in, int fq_in) const {
;     ...
; #pragma unroll
;         for (int ai = 0; ai < 2; ++ai)
; #pragma unroll
;             for (int m = 0; m < 4; ++m) {
;                 const int row = u.pm * BM + ai * 128 + wr * 64 + m * 16 + fr;
;                 float s = 0.f;
; #pragma unroll
;                 for (int bj = 0; bj < 2; ++bj) {
;                     const size_t off = (size_t)row * DM + u.pn * BM + bj * HALF + wc * 32 + 8 * fq;
;                     f32x4 b0, b1;
;                     if (xbase) { b0 = *(const f32x4*)(xbase + off); b1 = *(const f32x4*)(xbase + off + 4); }
;                     else { const u32x4 q = *(const u32x4*)(hb + off);
;                         b0 = (f32x4){BF16_LO(q.x), BF16_HI(q.x), BF16_LO(q.y), BF16_HI(q.y)}; b1 = (f32x4){BF16_LO(q.z), BF16_HI(q.z), BF16_LO(q.w), BF16_HI(q.w)}; }
;                     const f32x4 h0 = b0 + acc[ai][bj][m][0], h1 = b1 + acc[ai][bj][m][1];
;                     u32x4 w; w.x = pk2(h0[0], h0[1]); w.y = pk2(h0[2], h0[3]); w.z = pk2(h1[0], h1[1]); w.w = pk2(h1[2], h1[3]);
;                     *(u32x4*)(hb + off) = w;
;                     s += (h0[0] * h0[0] + h0[1] * h0[1]) + (h0[2] * h0[2] + h0[3] * h0[3]) + (h1[0] * h1[0] + h1[1] * h1[1]) + (h1[2] * h1[2] + h1[3] * h1[3]);
;                 }
;                 s = xor32_sum(xor16_sum(s));
;                 if (fq == 0) xch[(ai * 128 + wr * 64 + m * 16 + fr) * 4 + wc] = s;
;                 if (m == 3) asm volatile("" ::: "memory");
.LBB0_1736:
	v_mov_b32_e32 v169, v148
	v_mov_b32_e32 v168, v149
	s_lshl_b32 s4, s54, 8
	v_add_u32_e32 v188, s39, v168
	v_add_u32_e32 v144, s4, v188
	s_lshl_b32 s0, s53, 8
	s_ashr_i32 s1, s0, 31
	v_lshlrev_b32_e32 v146, 3, v169
	v_ashrrev_i32_e32 v145, 31, v144
	v_ashrrev_i32_e32 v147, 31, v146
	s_or_b64 s[0:1], s[0:1], s[14:15]
	v_lshlrev_b64 v[170:171], 11, v[144:145]
	v_lshl_add_u64 v[146:147], s[0:1], 0, v[146:147]
	v_lshl_add_u64 v[170:171], s[12:13], 0, v[170:171]
	v_lshl_add_u64 v[178:179], v[146:147], 1, v[170:171]
	global_load_dwordx4 v[170:173], v[178:179], off
	global_load_dwordx4 v[174:177], v[178:179], off offset:256
	v_add_u32_e32 v190, 16, v144
	v_ashrrev_i32_e32 v191, 31, v190
	v_lshlrev_b64 v[190:191], 11, v[190:191]
	v_lshl_add_u64 v[190:191], s[12:13], 0, v[190:191]
	v_lshl_add_u64 v[190:191], v[146:147], 1, v[190:191]
	global_load_dwordx4 v[192:195], v[190:191], off
	global_load_dwordx4 v[196:199], v[190:191], off offset:256
	v_add_u32_e32 v200, 32, v144
	v_ashrrev_i32_e32 v201, 31, v200
	v_lshlrev_b64 v[200:201], 11, v[200:201]
	v_lshl_add_u64 v[200:201], s[12:13], 0, v[200:201]
	v_lshl_add_u64 v[200:201], v[146:147], 1, v[200:201]
	global_load_dwordx4 v[202:205], v[200:201], off
	global_load_dwordx4 v[206:209], v[200:201], off offset:256
	v_add_u32_e32 v210, 48, v144
	v_ashrrev_i32_e32 v211, 31, v210
	v_lshlrev_b64 v[210:211], 11, v[210:211]
	v_lshl_add_u64 v[210:211], s[12:13], 0, v[210:211]
	v_lshl_add_u64 v[210:211], v[146:147], 1, v[210:211]
	global_load_dwordx4 v[212:215], v[210:211], off
	global_load_dwordx4 v[216:219], v[210:211], off offset:256
	v_add_u32_e32 v220, 0x80, v144
	v_ashrrev_i32_e32 v221, 31, v220
	v_lshlrev_b64 v[220:221], 11, v[220:221]
	v_lshl_add_u64 v[220:221], s[12:13], 0, v[220:221]
	v_lshl_add_u64 v[220:221], v[146:147], 1, v[220:221]
	global_load_dwordx4 v[222:225], v[220:221], off
	global_load_dwordx4 v[226:229], v[220:221], off offset:256
	v_add_u32_e32 v230, 0x90, v144
	v_ashrrev_i32_e32 v231, 31, v230
	v_lshlrev_b64 v[230:231], 11, v[230:231]
	v_lshl_add_u64 v[230:231], s[12:13], 0, v[230:231]
	v_lshl_add_u64 v[230:231], v[146:147], 1, v[230:231]
	global_load_dwordx4 v[232:235], v[230:231], off
	global_load_dwordx4 v[236:239], v[230:231], off offset:256
	v_add_u32_e32 v240, 0xa0, v144
	v_ashrrev_i32_e32 v241, 31, v240
	v_lshlrev_b64 v[240:241], 11, v[240:241]
	v_lshl_add_u64 v[240:241], s[12:13], 0, v[240:241]
	v_lshl_add_u64 v[240:241], v[146:147], 1, v[240:241]
	global_load_dwordx4 v[242:245], v[240:241], off
	global_load_dwordx4 v[246:249], v[240:241], off offset:256
	v_cmp_eq_u32_e32 vcc, 0, v169
	s_waitcnt vmcnt(12)
	v_lshlrev_b32_e32 v180, 16, v170
	v_and_b32_e32 v181, 0xffff0000, v170
	v_lshlrev_b32_e32 v170, 16, v171
	v_and_b32_e32 v171, 0xffff0000, v171
	v_lshlrev_b32_e32 v182, 16, v172
	v_and_b32_e32 v183, 0xffff0000, v172
	v_lshlrev_b32_e32 v172, 16, v173
	v_and_b32_e32 v173, 0xffff0000, v173
	v_lshlrev_b32_e32 v184, 16, v174
	v_and_b32_e32 v185, 0xffff0000, v174
	v_lshlrev_b32_e32 v174, 16, v175
	v_and_b32_e32 v175, 0xffff0000, v175
	v_lshlrev_b32_e32 v186, 16, v176
	v_and_b32_e32 v187, 0xffff0000, v176
	v_lshlrev_b32_e32 v176, 16, v177
	v_and_b32_e32 v177, 0xffff0000, v177
	v_pk_add_f32 v[126:127], v[126:127], v[170:171]
	v_pk_add_f32 v[124:125], v[124:125], v[180:181]
	v_pk_add_f32 v[122:123], v[122:123], v[172:173]
	v_pk_add_f32 v[170:171], v[118:119], v[174:175]
	v_pk_add_f32 v[172:173], v[116:117], v[184:185]
	v_pk_add_f32 v[120:121], v[120:121], v[182:183]
	v_pk_add_f32 v[174:175], v[114:115], v[176:177]
	v_pk_add_f32 v[176:177], v[112:113], v[186:187]
	v_cvt_pk_bf16_f32 v112, v124, v125
	v_cvt_pk_bf16_f32 v113, v126, v127
	v_mul_f32_e32 v125, v125, v125
	v_mul_f32_e32 v127, v127, v127
	v_mul_f32_e32 v145, v173, v173
	v_mul_f32_e32 v169, v171, v171
	v_cvt_pk_bf16_f32 v114, v120, v121
	v_cvt_pk_bf16_f32 v115, v122, v123
	v_mul_f32_e32 v121, v121, v121
	v_cvt_pk_bf16_f32 v117, v170, v171
	v_mul_f32_e32 v171, v177, v177
	v_fmac_f32_e32 v125, v124, v124
	v_fmac_f32_e32 v127, v126, v126
	v_fmac_f32_e32 v145, v172, v172
	v_fmac_f32_e32 v169, v170, v170
	v_mul_f32_e32 v123, v123, v123
	v_cvt_pk_bf16_f32 v116, v172, v173
	v_mul_f32_e32 v173, v175, v175
	global_store_dwordx4 v[178:179], v[112:115], off
	v_fmac_f32_e32 v121, v120, v120
	v_fmac_f32_e32 v171, v176, v176
	v_add_f32_e32 v112, v125, v127
	v_add_f32_e32 v113, v145, v169
	v_fmac_f32_e32 v123, v122, v122
	v_fmac_f32_e32 v173, v174, v174
	v_add_f32_e32 v112, v121, v112
	v_add_f32_e32 v113, v171, v113
	v_add_f32_e32 v112, v123, v112
	v_add_f32_e32 v113, v173, v113
	v_add_f32_e32 v112, v112, v113
	v_mov_b32_e32 v113, v112
	s_nop 1
	v_permlane16_swap_b32_e32 v112, v113
	v_add_f32_e32 v113, v112, v113
	v_mov_b32_e32 v114, v113
	v_cvt_pk_bf16_f32 v118, v176, v177
	v_cvt_pk_bf16_f32 v119, v174, v175
	v_permlane32_swap_b32_e32 v113, v114
	v_lshl_add_u32 v112, v188, 4, s47
	global_store_dwordx4 v[178:179], v[116:119], off offset:256
	s_and_saveexec_b64 s[0:1], vcc
	v_add_f32_e32 v113, v113, v114
	ds_write_b32 v112, v113
	s_or_b64 exec, exec, s[0:1]
	s_waitcnt vmcnt(13)
	v_lshlrev_b32_e32 v124, 16, v192
	v_and_b32_e32 v125, 0xffff0000, v192
	v_lshlrev_b32_e32 v114, 16, v193
	v_and_b32_e32 v115, 0xffff0000, v193
	v_lshlrev_b32_e32 v126, 16, v194
	v_and_b32_e32 v127, 0xffff0000, v194
	v_lshlrev_b32_e32 v116, 16, v195
	v_and_b32_e32 v117, 0xffff0000, v195
	s_waitcnt vmcnt(12)
; __device__ __forceinline__ unsigned pk2(float lo, float hi) { f32x2_t v = {lo, hi}; bf16x2_t b = __builtin_convertvector(v, bf16x2_t); return __builtin_bit_cast(unsigned, b); }
; __device__ __forceinline__ float xor16_sum(float v) { const auto r = __builtin_amdgcn_permlane16_swap(__float_as_uint(v), __float_as_uint(v), false, false); return __uint_as_float(r[0]) + __uint_as_float(r[1]); }
; __device__ __forceinline__ float xor32_sum(float v) { const auto r = __builtin_amdgcn_permlane32_swap(__float_as_uint(v), __float_as_uint(v), false, false); return __uint_as_float(r[0]) + __uint_as_float(r[1]); }
; #define BF16_LO(w) __uint_as_float((w) << 16)
; #define BF16_HI(w) __uint_as_float((w) & 0xffff0000u)
;     __device__ __forceinline__ void operator()(const f32x4 (&acc)[2][2][4][2], const Unit& u, int wr, int wc, int fr_in, int fq_in) const {
;     ...
; #pragma unroll
;         for (int ai = 0; ai < 2; ++ai)
; #pragma unroll
;             for (int m = 0; m < 4; ++m) {
;                 const int row = u.pm * BM + ai * 128 + wr * 64 + m * 16 + fr;
;                 float s = 0.f;
; #pragma unroll
;                 for (int bj = 0; bj < 2; ++bj) {
;                     const size_t off = (size_t)row * DM + u.pn * BM + bj * HALF + wc * 32 + 8 * fq;
;                     f32x4 b0, b1;
;                     if (xbase) { b0 = *(const f32x4*)(xbase + off); b1 = *(const f32x4*)(xbase + off + 4); }
;                     else { const u32x4 q = *(const u32x4*)(hb + off);
;                         b0 = (f32x4){BF16_LO(q.x), BF16_HI(q.x), BF16_LO(q.y), BF16_HI(q.y)}; b1 = (f32x4){BF16_LO(q.z), BF16_HI(q.z), BF16_LO(q.w), BF16_HI(q.w)}; }
;                     const f32x4 h0 = b0 + acc[ai][bj][m][0], h1 = b1 + acc[ai][bj][m][1];
;                     u32x4 w; w.x = pk2(h0[0], h0[1]); w.y = pk2(h0[2], h0[3]); w.z = pk2(h1[0], h1[1]); w.w = pk2(h1[2], h1[3]);
;                     *(u32x4*)(hb + off) = w;
;                     s += (h0[0] * h0[0] + h0[1] * h0[1]) + (h0[2] * h0[2] + h0[3] * h0[3]) + (h1[0] * h1[0] + h1[1] * h1[1]) + (h1[2] * h1[2] + h1[3] * h1[3]);
;                 }
;                 s = xor32_sum(xor16_sum(s));
;                 if (fq == 0) xch[(ai * 128 + wr * 64 + m * 16 + fr) * 4 + wc] = s;
;                 if (m == 3) asm volatile("" ::: "memory");
	v_lshlrev_b32_e32 v170, 16, v196
	v_and_b32_e32 v171, 0xffff0000, v196
	v_lshlrev_b32_e32 v118, 16, v197
	v_and_b32_e32 v119, 0xffff0000, v197
	v_lshlrev_b32_e32 v172, 16, v198
	v_and_b32_e32 v173, 0xffff0000, v198
	v_lshlrev_b32_e32 v120, 16, v199
	v_and_b32_e32 v121, 0xffff0000, v199
	v_pk_add_f32 v[110:111], v[110:111], v[114:115]
	v_pk_add_f32 v[108:109], v[108:109], v[124:125]
	v_pk_add_f32 v[106:107], v[106:107], v[116:117]
	v_pk_add_f32 v[114:115], v[102:103], v[118:119]
	v_pk_add_f32 v[116:117], v[100:101], v[170:171]
	v_pk_add_f32 v[104:105], v[104:105], v[126:127]
	v_pk_add_f32 v[118:119], v[98:99], v[120:121]
	v_pk_add_f32 v[120:121], v[96:97], v[172:173]
	v_cvt_pk_bf16_f32 v96, v108, v109
	v_cvt_pk_bf16_f32 v97, v110, v111
	v_mul_f32_e32 v109, v109, v109
	v_mul_f32_e32 v111, v111, v111
	v_cvt_pk_bf16_f32 v101, v114, v115
	v_mul_f32_e32 v113, v117, v117
	v_mul_f32_e32 v115, v115, v115
	v_cvt_pk_bf16_f32 v98, v104, v105
	v_cvt_pk_bf16_f32 v99, v106, v107
	v_mul_f32_e32 v105, v105, v105
	v_cvt_pk_bf16_f32 v100, v116, v117
	v_mul_f32_e32 v117, v121, v121
	v_fmac_f32_e32 v109, v108, v108
	v_fmac_f32_e32 v111, v110, v110
	v_fmac_f32_e32 v113, v116, v116
	v_fmac_f32_e32 v115, v114, v114
	v_mul_f32_e32 v107, v107, v107
	v_cvt_pk_bf16_f32 v103, v118, v119
	v_mul_f32_e32 v119, v119, v119
	global_store_dwordx4 v[190:191], v[96:99], off
	v_fmac_f32_e32 v105, v104, v104
	v_fmac_f32_e32 v117, v120, v120
	v_add_f32_e32 v96, v109, v111
	v_add_f32_e32 v97, v113, v115
	v_fmac_f32_e32 v107, v106, v106
	v_fmac_f32_e32 v119, v118, v118
	v_add_f32_e32 v96, v105, v96
	v_add_f32_e32 v97, v117, v97
	v_add_f32_e32 v96, v107, v96
	v_add_f32_e32 v97, v119, v97
	v_add_f32_e32 v96, v96, v97
	v_mov_b32_e32 v97, v96
	s_nop 1
	v_permlane16_swap_b32_e32 v96, v97
	v_add_f32_e32 v96, v96, v97
	v_mov_b32_e32 v97, v96
	v_cvt_pk_bf16_f32 v102, v120, v121
	s_nop 0
	v_permlane32_swap_b32_e32 v96, v97
	global_store_dwordx4 v[190:191], v[100:103], off offset:256
	s_and_saveexec_b64 s[0:1], vcc
	v_add_f32_e32 v96, v96, v97
	ds_write_b32 v112, v96 offset:256
	s_or_b64 exec, exec, s[0:1]
	s_waitcnt vmcnt(13)
	v_lshlrev_b32_e32 v106, 16, v202
	v_and_b32_e32 v107, 0xffff0000, v202
	v_lshlrev_b32_e32 v96, 16, v203
	v_and_b32_e32 v97, 0xffff0000, v203
	v_lshlrev_b32_e32 v108, 16, v204
	v_and_b32_e32 v109, 0xffff0000, v204
	v_lshlrev_b32_e32 v98, 16, v205
	v_and_b32_e32 v99, 0xffff0000, v205
	s_waitcnt vmcnt(12)
	v_lshlrev_b32_e32 v110, 16, v206
	v_and_b32_e32 v111, 0xffff0000, v206
	v_lshlrev_b32_e32 v100, 16, v207
	v_and_b32_e32 v101, 0xffff0000, v207
	v_lshlrev_b32_e32 v114, 16, v208
	v_and_b32_e32 v115, 0xffff0000, v208
	v_lshlrev_b32_e32 v102, 16, v209
	v_and_b32_e32 v103, 0xffff0000, v209
	v_pk_add_f32 v[94:95], v[94:95], v[96:97]
	v_pk_add_f32 v[92:93], v[92:93], v[106:107]
	v_pk_add_f32 v[90:91], v[90:91], v[98:99]
	v_pk_add_f32 v[96:97], v[86:87], v[100:101]
	v_pk_add_f32 v[98:99], v[84:85], v[110:111]
	v_pk_add_f32 v[88:89], v[88:89], v[108:109]
	v_pk_add_f32 v[100:101], v[82:83], v[102:103]
	v_pk_add_f32 v[102:103], v[80:81], v[114:115]
	v_cvt_pk_bf16_f32 v80, v92, v93
	v_cvt_pk_bf16_f32 v81, v94, v95
	v_mul_f32_e32 v93, v93, v93
	v_mul_f32_e32 v95, v95, v95
	v_cvt_pk_bf16_f32 v84, v98, v99
	v_cvt_pk_bf16_f32 v85, v96, v97
	v_mul_f32_e32 v99, v99, v99
	v_mul_f32_e32 v97, v97, v97
	v_cvt_pk_bf16_f32 v82, v88, v89
	v_cvt_pk_bf16_f32 v83, v90, v91
	v_mul_f32_e32 v89, v89, v89
	v_cvt_pk_bf16_f32 v86, v102, v103
	v_mul_f32_e32 v103, v103, v103
	v_fmac_f32_e32 v93, v92, v92
	v_fmac_f32_e32 v95, v94, v94
	v_fmac_f32_e32 v99, v98, v98
	v_fmac_f32_e32 v97, v96, v96
	v_mul_f32_e32 v91, v91, v91
	v_cvt_pk_bf16_f32 v87, v100, v101
	v_mul_f32_e32 v101, v101, v101
	global_store_dwordx4 v[200:201], v[80:83], off
	v_fmac_f32_e32 v89, v88, v88
	v_fmac_f32_e32 v103, v102, v102
	v_add_f32_e32 v80, v93, v95
	v_add_f32_e32 v81, v99, v97
	v_fmac_f32_e32 v91, v90, v90
	v_fmac_f32_e32 v101, v100, v100
	v_add_f32_e32 v80, v89, v80
	v_add_f32_e32 v81, v103, v81
	v_add_f32_e32 v80, v91, v80
	v_add_f32_e32 v81, v101, v81
	v_add_f32_e32 v80, v80, v81
	v_mov_b32_e32 v81, v80
	s_nop 1
	v_permlane16_swap_b32_e32 v80, v81
	v_add_f32_e32 v80, v80, v81
	v_mov_b32_e32 v81, v80
	s_nop 1
	v_permlane32_swap_b32_e32 v80, v81
	global_store_dwordx4 v[200:201], v[84:87], off offset:256
	s_and_saveexec_b64 s[0:1], vcc
	v_add_f32_e32 v80, v80, v81
	ds_write_b32 v112, v80 offset:512
	s_or_b64 exec, exec, s[0:1]
	s_waitcnt vmcnt(13)
	v_lshlrev_b32_e32 v90, 16, v212
	v_and_b32_e32 v91, 0xffff0000, v212
	v_lshlrev_b32_e32 v80, 16, v213
	v_and_b32_e32 v81, 0xffff0000, v213
	v_lshlrev_b32_e32 v92, 16, v214
	v_and_b32_e32 v93, 0xffff0000, v214
	v_lshlrev_b32_e32 v82, 16, v215
	v_and_b32_e32 v83, 0xffff0000, v215
	s_waitcnt vmcnt(12)
; __device__ __forceinline__ unsigned pk2(float lo, float hi) { f32x2_t v = {lo, hi}; bf16x2_t b = __builtin_convertvector(v, bf16x2_t); return __builtin_bit_cast(unsigned, b); }
; __device__ __forceinline__ float xor16_sum(float v) { const auto r = __builtin_amdgcn_permlane16_swap(__float_as_uint(v), __float_as_uint(v), false, false); return __uint_as_float(r[0]) + __uint_as_float(r[1]); }
; __device__ __forceinline__ float xor32_sum(float v) { const auto r = __builtin_amdgcn_permlane32_swap(__float_as_uint(v), __float_as_uint(v), false, false); return __uint_as_float(r[0]) + __uint_as_float(r[1]); }
; #define BF16_LO(w) __uint_as_float((w) << 16)
; #define BF16_HI(w) __uint_as_float((w) & 0xffff0000u)
;     __device__ __forceinline__ void operator()(const f32x4 (&acc)[2][2][4][2], const Unit& u, int wr, int wc, int fr_in, int fq_in) const {
;     ...
; #pragma unroll
;         for (int ai = 0; ai < 2; ++ai)
; #pragma unroll
;             for (int m = 0; m < 4; ++m) {
;                 const int row = u.pm * BM + ai * 128 + wr * 64 + m * 16 + fr;
;                 float s = 0.f;
; #pragma unroll
;                 for (int bj = 0; bj < 2; ++bj) {
;                     const size_t off = (size_t)row * DM + u.pn * BM + bj * HALF + wc * 32 + 8 * fq;
;                     f32x4 b0, b1;
;                     if (xbase) { b0 = *(const f32x4*)(xbase + off); b1 = *(const f32x4*)(xbase + off + 4); }
;                     else { const u32x4 q = *(const u32x4*)(hb + off);
;                         b0 = (f32x4){BF16_LO(q.x), BF16_HI(q.x), BF16_LO(q.y), BF16_HI(q.y)}; b1 = (f32x4){BF16_LO(q.z), BF16_HI(q.z), BF16_LO(q.w), BF16_HI(q.w)}; }
;                     const f32x4 h0 = b0 + acc[ai][bj][m][0], h1 = b1 + acc[ai][bj][m][1];
;                     u32x4 w; w.x = pk2(h0[0], h0[1]); w.y = pk2(h0[2], h0[3]); w.z = pk2(h1[0], h1[1]); w.w = pk2(h1[2], h1[3]);
;                     *(u32x4*)(hb + off) = w;
;                     s += (h0[0] * h0[0] + h0[1] * h0[1]) + (h0[2] * h0[2] + h0[3] * h0[3]) + (h1[0] * h1[0] + h1[1] * h1[1]) + (h1[2] * h1[2] + h1[3] * h1[3]);
;                 }
;                 s = xor32_sum(xor16_sum(s));
;                 if (fq == 0) xch[(ai * 128 + wr * 64 + m * 16 + fr) * 4 + wc] = s;
;                 if (m == 3) asm volatile("" ::: "memory");
	v_lshlrev_b32_e32 v94, 16, v216
	v_and_b32_e32 v95, 0xffff0000, v216
	v_lshlrev_b32_e32 v84, 16, v217
	v_and_b32_e32 v85, 0xffff0000, v217
	v_lshlrev_b32_e32 v96, 16, v218
	v_and_b32_e32 v97, 0xffff0000, v218
	v_lshlrev_b32_e32 v86, 16, v219
	v_and_b32_e32 v87, 0xffff0000, v219
	v_pk_add_f32 v[78:79], v[78:79], v[80:81]
	v_pk_add_f32 v[76:77], v[76:77], v[90:91]
	v_pk_add_f32 v[74:75], v[74:75], v[82:83]
	v_pk_add_f32 v[80:81], v[70:71], v[84:85]
	v_pk_add_f32 v[82:83], v[68:69], v[94:95]
	v_pk_add_f32 v[72:73], v[72:73], v[92:93]
	v_pk_add_f32 v[84:85], v[66:67], v[86:87]
	v_pk_add_f32 v[86:87], v[64:65], v[96:97]
	v_cvt_pk_bf16_f32 v64, v76, v77
	v_cvt_pk_bf16_f32 v65, v78, v79
	v_mul_f32_e32 v77, v77, v77
	v_mul_f32_e32 v79, v79, v79
	v_cvt_pk_bf16_f32 v68, v82, v83
	v_cvt_pk_bf16_f32 v69, v80, v81
	v_mul_f32_e32 v83, v83, v83
	v_mul_f32_e32 v81, v81, v81
	v_cvt_pk_bf16_f32 v66, v72, v73
	v_cvt_pk_bf16_f32 v67, v74, v75
	v_mul_f32_e32 v73, v73, v73
	v_cvt_pk_bf16_f32 v70, v86, v87
	v_mul_f32_e32 v87, v87, v87
	v_fmac_f32_e32 v77, v76, v76
	v_fmac_f32_e32 v79, v78, v78
	v_fmac_f32_e32 v83, v82, v82
	v_fmac_f32_e32 v81, v80, v80
	v_mul_f32_e32 v75, v75, v75
	v_cvt_pk_bf16_f32 v71, v84, v85
	v_mul_f32_e32 v85, v85, v85
	global_store_dwordx4 v[210:211], v[64:67], off
	v_fmac_f32_e32 v73, v72, v72
	v_fmac_f32_e32 v87, v86, v86
	v_add_f32_e32 v64, v77, v79
	v_add_f32_e32 v65, v83, v81
	v_fmac_f32_e32 v75, v74, v74
	v_fmac_f32_e32 v85, v84, v84
	v_add_f32_e32 v64, v73, v64
	v_add_f32_e32 v65, v87, v65
	v_add_f32_e32 v64, v75, v64
	v_add_f32_e32 v65, v85, v65
	v_add_f32_e32 v64, v64, v65
	v_mov_b32_e32 v65, v64
	s_nop 1
	v_permlane16_swap_b32_e32 v64, v65
	v_add_f32_e32 v64, v64, v65
	v_mov_b32_e32 v65, v64
	s_nop 1
	v_permlane32_swap_b32_e32 v64, v65
	global_store_dwordx4 v[210:211], v[68:71], off offset:256
	s_and_saveexec_b64 s[0:1], vcc
	v_add_f32_e32 v64, v64, v65
	ds_write_b32 v112, v64 offset:768
	s_or_b64 exec, exec, s[0:1]
	s_waitcnt vmcnt(13)
	v_lshlrev_b32_e32 v74, 16, v222
	v_and_b32_e32 v75, 0xffff0000, v222
	v_lshlrev_b32_e32 v64, 16, v223
	v_and_b32_e32 v65, 0xffff0000, v223
	v_lshlrev_b32_e32 v76, 16, v224
	v_and_b32_e32 v77, 0xffff0000, v224
	v_lshlrev_b32_e32 v66, 16, v225
	v_and_b32_e32 v67, 0xffff0000, v225
	s_waitcnt vmcnt(12)
	v_lshlrev_b32_e32 v78, 16, v226
	v_and_b32_e32 v79, 0xffff0000, v226
	v_lshlrev_b32_e32 v68, 16, v227
	v_and_b32_e32 v69, 0xffff0000, v227
	v_lshlrev_b32_e32 v80, 16, v228
	v_and_b32_e32 v81, 0xffff0000, v228
	v_lshlrev_b32_e32 v70, 16, v229
	v_and_b32_e32 v71, 0xffff0000, v229
	v_pk_add_f32 v[62:63], v[62:63], v[64:65]
	v_pk_add_f32 v[60:61], v[60:61], v[74:75]
	v_pk_add_f32 v[58:59], v[58:59], v[66:67]
	v_pk_add_f32 v[64:65], v[54:55], v[68:69]
	v_pk_add_f32 v[66:67], v[52:53], v[78:79]
	v_pk_add_f32 v[56:57], v[56:57], v[76:77]
	v_pk_add_f32 v[68:69], v[50:51], v[70:71]
	v_pk_add_f32 v[70:71], v[48:49], v[80:81]
	v_cvt_pk_bf16_f32 v48, v60, v61
	v_cvt_pk_bf16_f32 v49, v62, v63
	v_mul_f32_e32 v61, v61, v61
	v_mul_f32_e32 v63, v63, v63
	v_cvt_pk_bf16_f32 v52, v66, v67
	v_cvt_pk_bf16_f32 v53, v64, v65
	v_mul_f32_e32 v67, v67, v67
	v_mul_f32_e32 v65, v65, v65
	v_cvt_pk_bf16_f32 v50, v56, v57
	v_cvt_pk_bf16_f32 v51, v58, v59
	v_mul_f32_e32 v57, v57, v57
	v_cvt_pk_bf16_f32 v54, v70, v71
	v_mul_f32_e32 v71, v71, v71
	v_fmac_f32_e32 v61, v60, v60
	v_fmac_f32_e32 v63, v62, v62
	v_fmac_f32_e32 v67, v66, v66
	v_fmac_f32_e32 v65, v64, v64
	v_mul_f32_e32 v59, v59, v59
	v_cvt_pk_bf16_f32 v55, v68, v69
	v_mul_f32_e32 v69, v69, v69
	global_store_dwordx4 v[220:221], v[48:51], off
	v_fmac_f32_e32 v57, v56, v56
	v_fmac_f32_e32 v71, v70, v70
	v_add_f32_e32 v48, v61, v63
	v_add_f32_e32 v49, v67, v65
	v_fmac_f32_e32 v59, v58, v58
	v_fmac_f32_e32 v69, v68, v68
	v_add_f32_e32 v48, v57, v48
	v_add_f32_e32 v49, v71, v49
	v_add_f32_e32 v48, v59, v48
	v_add_f32_e32 v49, v69, v49
	v_add_f32_e32 v48, v48, v49
	v_mov_b32_e32 v49, v48
	s_nop 1
	v_permlane16_swap_b32_e32 v48, v49
	v_add_f32_e32 v48, v48, v49
	v_mov_b32_e32 v49, v48
	s_nop 1
	v_permlane32_swap_b32_e32 v48, v49
	global_store_dwordx4 v[220:221], v[52:55], off offset:256
	s_and_saveexec_b64 s[0:1], vcc
	v_add_f32_e32 v48, v48, v49
	ds_write_b32 v112, v48 offset:2048
	s_or_b64 exec, exec, s[0:1]
	s_waitcnt vmcnt(13)
	v_lshlrev_b32_e32 v58, 16, v232
	v_and_b32_e32 v59, 0xffff0000, v232
	v_lshlrev_b32_e32 v48, 16, v233
	v_and_b32_e32 v49, 0xffff0000, v233
	v_lshlrev_b32_e32 v60, 16, v234
	v_and_b32_e32 v61, 0xffff0000, v234
	v_lshlrev_b32_e32 v50, 16, v235
	v_and_b32_e32 v51, 0xffff0000, v235
	s_waitcnt vmcnt(12)
	v_lshlrev_b32_e32 v62, 16, v236
	v_and_b32_e32 v63, 0xffff0000, v236
	v_lshlrev_b32_e32 v52, 16, v237
	v_and_b32_e32 v53, 0xffff0000, v237
	v_lshlrev_b32_e32 v64, 16, v238
	v_and_b32_e32 v65, 0xffff0000, v238
	v_lshlrev_b32_e32 v54, 16, v239
	v_and_b32_e32 v55, 0xffff0000, v239
	v_pk_add_f32 v[46:47], v[46:47], v[48:49]
	v_pk_add_f32 v[44:45], v[44:45], v[58:59]
	v_pk_add_f32 v[42:43], v[42:43], v[50:51]
	v_pk_add_f32 v[48:49], v[38:39], v[52:53]
	v_pk_add_f32 v[50:51], v[36:37], v[62:63]
	v_pk_add_f32 v[40:41], v[40:41], v[60:61]
	v_pk_add_f32 v[52:53], v[34:35], v[54:55]
	v_pk_add_f32 v[54:55], v[32:33], v[64:65]
	v_cvt_pk_bf16_f32 v32, v44, v45
	v_cvt_pk_bf16_f32 v33, v46, v47
	v_mul_f32_e32 v45, v45, v45
	v_mul_f32_e32 v47, v47, v47
	v_cvt_pk_bf16_f32 v36, v50, v51
	v_cvt_pk_bf16_f32 v37, v48, v49
	v_mul_f32_e32 v51, v51, v51
	v_mul_f32_e32 v49, v49, v49
	v_cvt_pk_bf16_f32 v34, v40, v41
	v_cvt_pk_bf16_f32 v35, v42, v43
	v_mul_f32_e32 v41, v41, v41
	v_cvt_pk_bf16_f32 v38, v54, v55
	v_mul_f32_e32 v55, v55, v55
	v_fmac_f32_e32 v45, v44, v44
	v_fmac_f32_e32 v47, v46, v46
	v_fmac_f32_e32 v51, v50, v50
	v_fmac_f32_e32 v49, v48, v48
	v_mul_f32_e32 v43, v43, v43
	v_cvt_pk_bf16_f32 v39, v52, v53
	v_mul_f32_e32 v53, v53, v53
	global_store_dwordx4 v[230:231], v[32:35], off
	v_fmac_f32_e32 v41, v40, v40
	v_fmac_f32_e32 v55, v54, v54
	v_add_f32_e32 v32, v45, v47
	v_add_f32_e32 v33, v51, v49
	v_fmac_f32_e32 v43, v42, v42
	v_fmac_f32_e32 v53, v52, v52
	v_add_f32_e32 v32, v41, v32
	v_add_f32_e32 v33, v55, v33
	v_add_f32_e32 v32, v43, v32
	v_add_f32_e32 v33, v53, v33
	v_add_f32_e32 v32, v32, v33
	v_mov_b32_e32 v33, v32
	s_nop 1
	v_permlane16_swap_b32_e32 v32, v33
	v_add_f32_e32 v32, v32, v33
	v_mov_b32_e32 v33, v32
	s_nop 1
	v_permlane32_swap_b32_e32 v32, v33
	global_store_dwordx4 v[230:231], v[36:39], off offset:256
	s_and_saveexec_b64 s[0:1], vcc
	v_add_f32_e32 v32, v32, v33
	ds_write_b32 v112, v32 offset:2304
	s_or_b64 exec, exec, s[0:1]
	s_waitcnt vmcnt(13)
; __device__ __forceinline__ unsigned pk2(float lo, float hi) { f32x2_t v = {lo, hi}; bf16x2_t b = __builtin_convertvector(v, bf16x2_t); return __builtin_bit_cast(unsigned, b); }
; __device__ __forceinline__ float xor16_sum(float v) { const auto r = __builtin_amdgcn_permlane16_swap(__float_as_uint(v), __float_as_uint(v), false, false); return __uint_as_float(r[0]) + __uint_as_float(r[1]); }
;     __device__ __forceinline__ void operator()(const f32x4 (&acc)[2][2][4][2], const Unit& u, int wr, int wc, int fr_in, int fq_in) const {
;     ...
; #pragma unroll
;         for (int ai = 0; ai < 2; ++ai)
; #pragma unroll
;             for (int m = 0; m < 4; ++m) {
;                 const int row = u.pm * BM + ai * 128 + wr * 64 + m * 16 + fr;
;                 float s = 0.f;
; #pragma unroll
;                 for (int bj = 0; bj < 2; ++bj) {
;                     const size_t off = (size_t)row * DM + u.pn * BM + bj * HALF + wc * 32 + 8 * fq;
;                     f32x4 b0, b1;
;                     if (xbase) { b0 = *(const f32x4*)(xbase + off); b1 = *(const f32x4*)(xbase + off + 4); }
;                     else { const u32x4 q = *(const u32x4*)(hb + off);
;                         b0 = (f32x4){BF16_LO(q.x), BF16_HI(q.x), BF16_LO(q.y), BF16_HI(q.y)}; b1 = (f32x4){BF16_LO(q.z), BF16_HI(q.z), BF16_LO(q.w), BF16_HI(q.w)}; }
;                     const f32x4 h0 = b0 + acc[ai][bj][m][0], h1 = b1 + acc[ai][bj][m][1];
;                     u32x4 w; w.x = pk2(h0[0], h0[1]); w.y = pk2(h0[2], h0[3]); w.z = pk2(h1[0], h1[1]); w.w = pk2(h1[2], h1[3]);
;                     *(u32x4*)(hb + off) = w;
;                     s += (h0[0] * h0[0] + h0[1] * h0[1]) + (h0[2] * h0[2] + h0[3] * h0[3]) + (h1[0] * h1[0] + h1[1] * h1[1]) + (h1[2] * h1[2] + h1[3] * h1[3]);
;                 }
;                 s = xor32_sum(xor16_sum(s));
;                 if (fq == 0) xch[(ai * 128 + wr * 64 + m * 16 + fr) * 4 + wc] = s;
;                 if (m == 3) asm volatile("" ::: "memory");
;             }
;         PG8_EPI_BAR();
;         if (fq == 0) {
; #pragma unroll
;             for (int ai = 0; ai < 2; ++ai) {
;                 const int rl = ai * 128 + wr * 64 + wc * 16 + fr;
;                 const f32x4 p = *(const PG8_LAS f32x4*)(xch + rl * 4);
;                 const float t = (p[0] + p[1]) + (p[2] + p[3]);
;                 atomicAdd(rsq + u.pm * BM + rl, (u64_t)(t * 16777216.0f));
;             }
	v_lshlrev_b32_e32 v42, 16, v242
	v_and_b32_e32 v43, 0xffff0000, v242
	v_lshlrev_b32_e32 v32, 16, v243
	v_and_b32_e32 v33, 0xffff0000, v243
	v_lshlrev_b32_e32 v44, 16, v244
	v_and_b32_e32 v45, 0xffff0000, v244
	v_lshlrev_b32_e32 v34, 16, v245
	v_and_b32_e32 v35, 0xffff0000, v245
	s_waitcnt vmcnt(12)
	v_lshlrev_b32_e32 v46, 16, v246
	v_and_b32_e32 v47, 0xffff0000, v246
	v_lshlrev_b32_e32 v36, 16, v247
	v_and_b32_e32 v37, 0xffff0000, v247
	v_lshlrev_b32_e32 v48, 16, v248
	v_and_b32_e32 v49, 0xffff0000, v248
	v_lshlrev_b32_e32 v38, 16, v249
	v_and_b32_e32 v39, 0xffff0000, v249
	v_pk_add_f32 v[30:31], v[30:31], v[32:33]
	v_pk_add_f32 v[28:29], v[28:29], v[42:43]
	v_pk_add_f32 v[26:27], v[26:27], v[34:35]
	v_pk_add_f32 v[32:33], v[22:23], v[36:37]
	v_pk_add_f32 v[34:35], v[20:21], v[46:47]
	v_pk_add_f32 v[24:25], v[24:25], v[44:45]
	v_pk_add_f32 v[36:37], v[18:19], v[38:39]
	v_pk_add_f32 v[38:39], v[16:17], v[48:49]
	v_cvt_pk_bf16_f32 v16, v28, v29
	v_cvt_pk_bf16_f32 v17, v30, v31
	v_mul_f32_e32 v29, v29, v29
	v_mul_f32_e32 v31, v31, v31
	v_cvt_pk_bf16_f32 v20, v34, v35
	v_cvt_pk_bf16_f32 v21, v32, v33
	v_mul_f32_e32 v35, v35, v35
	v_mul_f32_e32 v33, v33, v33
	v_cvt_pk_bf16_f32 v18, v24, v25
	v_cvt_pk_bf16_f32 v19, v26, v27
	v_mul_f32_e32 v25, v25, v25
	v_cvt_pk_bf16_f32 v22, v38, v39
	v_mul_f32_e32 v39, v39, v39
	v_fmac_f32_e32 v29, v28, v28
	v_fmac_f32_e32 v31, v30, v30
	v_fmac_f32_e32 v35, v34, v34
	v_fmac_f32_e32 v33, v32, v32
	v_mul_f32_e32 v27, v27, v27
	v_cvt_pk_bf16_f32 v23, v36, v37
	v_mul_f32_e32 v37, v37, v37
	global_store_dwordx4 v[240:241], v[16:19], off
	v_fmac_f32_e32 v25, v24, v24
	v_fmac_f32_e32 v39, v38, v38
	v_add_f32_e32 v16, v29, v31
	v_add_f32_e32 v17, v35, v33
	v_fmac_f32_e32 v27, v26, v26
	v_fmac_f32_e32 v37, v36, v36
	v_add_f32_e32 v16, v25, v16
	v_add_f32_e32 v17, v39, v17
	v_add_f32_e32 v16, v27, v16
	v_add_f32_e32 v17, v37, v17
	v_add_f32_e32 v16, v16, v17
	v_mov_b32_e32 v17, v16
	s_nop 1
	v_permlane16_swap_b32_e32 v16, v17
	v_add_f32_e32 v16, v16, v17
	v_mov_b32_e32 v17, v16
	s_nop 1
	v_permlane32_swap_b32_e32 v16, v17
	global_store_dwordx4 v[240:241], v[20:23], off offset:256
	s_and_saveexec_b64 s[0:1], vcc
	v_add_f32_e32 v16, v16, v17
	ds_write_b32 v112, v16 offset:2560
	s_or_b64 exec, exec, s[0:1]
	v_add_u32_e32 v16, 0xb0, v144
	v_ashrrev_i32_e32 v17, 31, v16
	v_lshlrev_b64 v[16:17], 11, v[16:17]
	v_lshl_add_u64 v[16:17], s[12:13], 0, v[16:17]
	v_lshl_add_u64 v[24:25], v[146:147], 1, v[16:17]
	global_load_dwordx4 v[16:19], v[24:25], off
	global_load_dwordx4 v[20:23], v[24:25], off offset:256
	s_waitcnt vmcnt(1)
	v_lshlrev_b32_e32 v26, 16, v16
	v_and_b32_e32 v27, 0xffff0000, v16
	v_lshlrev_b32_e32 v16, 16, v17
	v_and_b32_e32 v17, 0xffff0000, v17
	v_lshlrev_b32_e32 v28, 16, v18
	v_and_b32_e32 v29, 0xffff0000, v18
	v_lshlrev_b32_e32 v18, 16, v19
	v_and_b32_e32 v19, 0xffff0000, v19
	s_waitcnt vmcnt(0)
	v_lshlrev_b32_e32 v30, 16, v20
	v_and_b32_e32 v31, 0xffff0000, v20
	v_lshlrev_b32_e32 v20, 16, v21
	v_and_b32_e32 v21, 0xffff0000, v21
	v_lshlrev_b32_e32 v32, 16, v22
	v_and_b32_e32 v33, 0xffff0000, v22
	v_lshlrev_b32_e32 v22, 16, v23
	v_and_b32_e32 v23, 0xffff0000, v23
	v_pk_add_f32 v[14:15], v[14:15], v[16:17]
	v_pk_add_f32 v[12:13], v[12:13], v[26:27]
	v_pk_add_f32 v[10:11], v[10:11], v[18:19]
	v_pk_add_f32 v[16:17], v[6:7], v[20:21]
	v_pk_add_f32 v[18:19], v[4:5], v[30:31]
	v_pk_add_f32 v[8:9], v[8:9], v[28:29]
	v_pk_add_f32 v[20:21], v[2:3], v[22:23]
	v_pk_add_f32 v[22:23], v[0:1], v[32:33]
	v_cvt_pk_bf16_f32 v0, v12, v13
	v_cvt_pk_bf16_f32 v1, v14, v15
	v_mul_f32_e32 v13, v13, v13
	v_mul_f32_e32 v15, v15, v15
	v_cvt_pk_bf16_f32 v4, v18, v19
	v_cvt_pk_bf16_f32 v5, v16, v17
	v_mul_f32_e32 v19, v19, v19
	v_mul_f32_e32 v17, v17, v17
	v_cvt_pk_bf16_f32 v2, v8, v9
	v_cvt_pk_bf16_f32 v3, v10, v11
	v_mul_f32_e32 v9, v9, v9
	v_cvt_pk_bf16_f32 v6, v22, v23
	v_mul_f32_e32 v23, v23, v23
	v_fmac_f32_e32 v13, v12, v12
	v_fmac_f32_e32 v15, v14, v14
	v_fmac_f32_e32 v19, v18, v18
	v_fmac_f32_e32 v17, v16, v16
	v_mul_f32_e32 v11, v11, v11
	v_cvt_pk_bf16_f32 v7, v20, v21
	v_mul_f32_e32 v21, v21, v21
	global_store_dwordx4 v[24:25], v[0:3], off
	v_fmac_f32_e32 v9, v8, v8
	v_fmac_f32_e32 v23, v22, v22
	v_add_f32_e32 v0, v13, v15
	v_add_f32_e32 v1, v19, v17
	v_fmac_f32_e32 v11, v10, v10
	v_fmac_f32_e32 v21, v20, v20
	v_add_f32_e32 v0, v9, v0
	v_add_f32_e32 v1, v23, v1
	v_add_f32_e32 v0, v11, v0
	v_add_f32_e32 v1, v21, v1
	v_add_f32_e32 v0, v0, v1
	v_mov_b32_e32 v1, v0
	s_nop 1
	v_permlane16_swap_b32_e32 v0, v1
	v_add_f32_e32 v0, v0, v1
	v_mov_b32_e32 v1, v0
	s_nop 1
	v_permlane32_swap_b32_e32 v0, v1
	global_store_dwordx4 v[24:25], v[4:7], off offset:256
	s_and_saveexec_b64 s[0:1], vcc
	v_add_f32_e32 v0, v0, v1
	ds_write_b32 v112, v0 offset:2816
	s_or_b64 exec, exec, s[0:1]
	s_waitcnt lgkmcnt(0)
	s_barrier
	s_and_saveexec_b64 s[0:1], vcc
	s_cbranch_execz .LBB0_1754
	v_add_u32_e32 v4, s46, v168
	v_lshl_add_u32 v6, v4, 4, v167
	ds_read_b128 v[0:3], v6
	s_ashr_i32 s5, s4, 31
	s_lshl_b64 s[4:5], s[4:5], 3
	s_add_u32 s4, s37, s4
	s_addc_u32 s5, s38, s5
	s_waitcnt lgkmcnt(0)
	v_add_f32_e32 v0, v0, v1
	v_add_f32_e32 v1, v2, v3
	v_add_f32_e32 v0, v0, v1
	v_mul_f32_e32 v0, 0x4b800000, v0
	v_trunc_f32_e32 v0, v0
	v_mul_f32_e32 v1, 0x2f800000, v0
	v_floor_f32_e32 v1, v1
	v_fmac_f32_e32 v0, 0xcf800000, v1
	v_cvt_u32_f32_e32 v0, v0
	v_cvt_u32_f32_e32 v1, v1
	v_ashrrev_i32_e32 v5, 31, v4
	v_lshl_add_u64 v[4:5], v[4:5], 3, s[4:5]
	global_atomic_add_x2 v[4:5], v[0:1], off
	ds_read_b128 v[0:3], v6 offset:2048
	s_waitcnt lgkmcnt(0)
	v_add_f32_e32 v0, v0, v1
	v_add_f32_e32 v1, v2, v3
	v_add_f32_e32 v0, v0, v1
	v_mul_f32_e32 v0, 0x4b800000, v0
	v_trunc_f32_e32 v0, v0
	v_mul_f32_e32 v1, 0x2f800000, v0
	v_floor_f32_e32 v1, v1
	v_fmac_f32_e32 v0, 0xcf800000, v1
	v_cvt_u32_f32_e32 v0, v0
	v_cvt_u32_f32_e32 v1, v1
	global_atomic_add_x2 v[4:5], v[0:1], off offset:1024
